# peepall + s_nop 0 restored at 16 v_cmp->v_cndmask sites (hazard row 18 pad that the removed v_max had provided)
# baseline (speedup 1.0000x reference)
.LBB0_1148:
	global_load_dwordx4 v[48:51], v[78:79], off
	global_load_dwordx4 v[44:47], v[82:83], off
	global_load_dwordx4 v[40:43], v[84:85], off
	v_mul_f32_e64 v58, |v56|, s69
	v_max_f32_e32 v59, v56, v56
	v_mul_f32_e64 v60, |v57|, s69
	v_exp_f32_e32 v67, v58
	v_min_f32_e32 v62, 0, v59
	v_exp_f32_e32 v59, v60
	v_max_f32_e32 v61, v57, v57
	v_mul_f32_e64 v66, |v55|, s69
	v_cmp_lt_f32_e32 vcc, 0, v57
	v_min_f32_e32 v63, 0, v61
	v_exp_f32_e32 v69, v66
	v_add_f32_e32 v66, 1.0, v67
	v_cndmask_b32_e32 v61, 1.0, v59, vcc
	v_cmp_lt_f32_e32 vcc, 0, v56
	v_add_f32_e32 v70, 1.0, v59
	v_cmp_gt_f32_e64 s[4:5], s74, v70
	v_cndmask_b32_e32 v60, 1.0, v67, vcc
	v_cmp_gt_f32_e32 vcc, s74, v66
	v_cndmask_b32_e64 v67, 0, 32, s[4:5]
	v_ldexp_f32 v67, v70, v67
	v_cndmask_b32_e64 v59, 0, 32, vcc
	v_ldexp_f32 v59, v66, v59
	v_log_f32_e32 v59, v59
	v_log_f32_e32 v67, v67
	v_mul_f32_e64 v64, |v54|, s69
	v_exp_f32_e32 v68, v64
	v_mul_f32_e32 v75, 0x3f317217, v59
	v_mul_f32_e32 v87, 0x3f317217, v67
	v_fma_f32 v75, v59, s75, -v75
	v_fma_f32 v87, v67, s75, -v87
	v_fmac_f32_e32 v75, 0x3377d1cf, v59
	v_rcp_f32_e32 v64, v66
	v_cndmask_b32_e32 v66, 0, v226, vcc
	v_fmac_f32_e32 v87, 0x3377d1cf, v67
	v_fmac_f32_e32 v75, 0x3f317217, v59
	v_cmp_lt_f32_e64 vcc, |v59|, s63
	v_max_f32_e32 v65, v54, v54
	v_add_f32_e32 v71, 1.0, v68
	v_fmac_f32_e32 v87, 0x3f317217, v67
	v_cndmask_b32_e32 v59, v59, v75, vcc
	v_cmp_lt_f32_e64 vcc, |v67|, s63
	v_min_f32_e32 v58, 0, v65
	v_rcp_f32_e32 v65, v70
	v_cmp_gt_f32_e64 s[6:7], s74, v71
	v_cndmask_b32_e64 v70, 0, v226, s[4:5]
	v_cndmask_b32_e32 v67, v67, v87, vcc
	v_cndmask_b32_e64 v73, 0, 32, s[6:7]
	v_sub_f32_e32 v66, v59, v66
	v_sub_f32_e32 v67, v67, v70
	v_ldexp_f32 v73, v71, v73
	v_pk_add_f32 v[62:63], v[62:63], v[66:67] neg_lo:[0,1] neg_hi:[0,1]
	v_log_f32_e32 v73, v73
	v_add_f32_e32 v72, 1.0, v69
	v_cndmask_b32_e64 v74, 0, v226, s[6:7]
	v_mul_f32_e32 v88, 0x3f317217, v73
	v_fma_f32 v88, v73, s75, -v88
	v_fmac_f32_e32 v88, 0x3377d1cf, v73
	v_fmac_f32_e32 v88, 0x3f317217, v73
	v_cmp_lt_f32_e64 vcc, |v73|, s63
	s_waitcnt vmcnt(2)
	v_pk_add_f32 v[62:63], v[62:63], v[48:49]
	s_waitcnt vmcnt(1)
	v_pk_add_f32 v[48:49], v[62:63], v[44:45] neg_lo:[0,1] neg_hi:[0,1]
	v_max_f32_e32 v59, v44, v44
	v_mul_f32_e64 v44, |v48|, s69
	v_max_f32_e32 v66, v45, v45
	v_mul_f32_e64 v45, |v49|, s69
	v_exp_f32_e32 v67, v44
	v_exp_f32_e32 v70, v45
	v_max_f32_e32 v44, v62, v59
	v_cndmask_b32_e32 v73, v73, v88, vcc
	v_add_f32_e32 v59, 1.0, v67
	v_add_f32_e32 v62, 1.0, v70
	v_cmp_gt_f32_e32 vcc, s74, v59
	v_max_f32_e32 v45, v63, v66
	v_cmp_gt_f32_e64 s[4:5], s74, v62
	v_cndmask_b32_e64 v63, 0, 32, vcc
	v_ldexp_f32 v59, v59, v63
	v_cndmask_b32_e64 v66, 0, 32, s[4:5]
	v_ldexp_f32 v62, v62, v66
	v_log_f32_e32 v59, v59
	v_log_f32_e32 v62, v62
	v_cndmask_b32_e32 v63, 0, v226, vcc
	v_cndmask_b32_e64 v66, 0, v226, s[4:5]
	v_mul_f32_e32 v67, 0x3f317217, v59
	v_mul_f32_e32 v70, 0x3f317217, v62
	v_fma_f32 v67, v59, s75, -v67
	v_fma_f32 v70, v62, s75, -v70
	v_fmac_f32_e32 v67, 0x3377d1cf, v59
	v_fmac_f32_e32 v70, 0x3377d1cf, v62
	v_fmac_f32_e32 v67, 0x3f317217, v59
	v_cmp_lt_f32_e64 vcc, |v59|, s63
	v_fmac_f32_e32 v70, 0x3f317217, v62
	s_waitcnt vmcnt(0)
	v_pk_mul_f32 v[40:41], v[60:61], v[40:41]
	v_cndmask_b32_e32 v59, v59, v67, vcc
	v_cmp_lt_f32_e64 vcc, |v62|, s63
	v_sub_f32_e32 v67, v59, v63
	v_pk_mul_f32 v[40:41], v[64:65], v[40:41]
	v_cndmask_b32_e32 v62, v62, v70, vcc
	v_cmp_gt_f32_e32 vcc, s74, v72
	v_sub_f32_e32 v66, v62, v66
	v_sub_f32_e32 v62, v73, v74
	v_cndmask_b32_e64 v59, 0, 32, vcc
	v_ldexp_f32 v59, v72, v59
	v_log_f32_e32 v63, v59
	v_max_f32_e32 v59, v55, v55
	v_min_f32_e32 v59, 0, v59
	v_rcp_f32_e32 v60, v71
	v_mul_f32_e32 v70, 0x3f317217, v63
	v_fma_f32 v70, v63, s75, -v70
	v_fmac_f32_e32 v70, 0x3377d1cf, v63
	v_fmac_f32_e32 v70, 0x3f317217, v63
	v_cmp_lt_f32_e64 s[4:5], |v63|, s63
	v_cvt_pk_bf16_f32 v40, v40, v41
	s_nop 0
	v_cndmask_b32_e64 v63, v63, v70, s[4:5]
	v_cndmask_b32_e32 v70, 0, v226, vcc
	v_sub_f32_e32 v63, v63, v70
	v_pk_add_f32 v[58:59], v[58:59], v[62:63] neg_lo:[0,1] neg_hi:[0,1]
	s_nop 0
	v_pk_add_f32 v[50:51], v[58:59], v[50:51]
	s_nop 0
	v_pk_add_f32 v[58:59], v[50:51], v[46:47] neg_lo:[0,1] neg_hi:[0,1]
	v_mul_f32_e64 v62, |v58|, s69
	v_exp_f32_e32 v62, v62
	v_mul_f32_e64 v63, |v59|, s69
	v_exp_f32_e32 v63, v63
	v_max_f32_e32 v46, v50, v46
	v_add_f32_e32 v61, 1.0, v62
	v_cmp_gt_f32_e32 vcc, s74, v61
	v_add_f32_e32 v63, 1.0, v63
	s_nop 0
	v_cndmask_b32_e64 v62, 0, 32, vcc
	v_ldexp_f32 v61, v61, v62
	v_log_f32_e32 v62, v61
	v_max_f32_e32 v47, v51, v47
	v_rcp_f32_e32 v61, v72
	v_mul_f32_e32 v50, 0x3f317217, v62
	v_fma_f32 v50, v62, s75, -v50
	v_fmac_f32_e32 v50, 0x3377d1cf, v62
	v_fmac_f32_e32 v50, 0x3f317217, v62
	v_cmp_lt_f32_e64 s[4:5], |v62|, s63
	s_nop 1
	v_cndmask_b32_e64 v50, v62, v50, s[4:5]
	v_cndmask_b32_e32 v62, 0, v226, vcc
	v_cmp_gt_f32_e32 vcc, s74, v63
	v_sub_f32_e32 v50, v50, v62
	s_nop 0
	v_cndmask_b32_e64 v64, 0, 32, vcc
	v_ldexp_f32 v63, v63, v64
	v_log_f32_e32 v63, v63
	v_cndmask_b32_e32 v62, 0, v226, vcc
	v_cmp_lt_f32_e64 vcc, |v49|, s49
	v_mul_f32_e32 v51, 0x3f317217, v63
	v_fma_f32 v51, v63, s75, -v51
	v_fmac_f32_e32 v51, 0x3377d1cf, v63
	v_fmac_f32_e32 v51, 0x3f317217, v63
	v_cmp_lt_f32_e64 s[4:5], |v63|, s63
	v_cndmask_b32_e32 v49, 0, v66, vcc
	v_cmp_lt_f32_e64 vcc, |v48|, s49
	v_cndmask_b32_e64 v51, v63, v51, s[4:5]
	v_sub_f32_e32 v51, v51, v62
	v_cndmask_b32_e32 v48, 0, v67, vcc
	v_cmp_lt_f32_e64 vcc, |v59|, s49
	v_pk_add_f32 v[44:45], v[44:45], v[48:49]
	s_nop 0
	v_cndmask_b32_e32 v51, 0, v51, vcc
	v_cmp_lt_f32_e64 vcc, |v58|, s49
	s_nop 1
	v_cndmask_b32_e32 v50, 0, v50, vcc
	v_cmp_lt_f32_e32 vcc, 0, v55
	v_pk_add_f32 v[46:47], v[46:47], v[50:51]
	s_nop 0
	v_cndmask_b32_e32 v49, 1.0, v69, vcc
	v_cmp_lt_f32_e32 vcc, 0, v54
	s_nop 1
	v_cndmask_b32_e32 v48, 1.0, v68, vcc
	v_pk_mul_f32 v[42:43], v[48:49], v[42:43]
	v_lshl_add_u64 v[48:49], v[52:53], 2, s[94:95]
	v_pk_mul_f32 v[42:43], v[60:61], v[42:43]
	global_store_dwordx4 v[48:49], v[44:47], off
	v_cvt_pk_bf16_f32 v41, v42, v43
	s_nop 0
	v_lshl_add_u64 v[44:45], v[52:53], 1, s[84:85]
	global_store_dwordx2 v[44:45], v[40:41], off

.LBB0_1213:
	v_mov_b32_e32 v195, v2
	v_or_b32_e32 v170, 4, v194
	v_or_b32_e32 v169, 8, v194
	v_or_b32_e32 v168, 12, v194
	s_and_b64 vcc, exec, s[2:3]
	s_cbranch_vccz .LBB0_1230
	s_mov_b64 s[0:1], -1
	s_and_b64 vcc, exec, s[14:15]
	s_cbranch_vccz .LBB0_1216
	v_lshlrev_b32_e32 v124, 2, v194
	global_load_dwordx4 v[160:163], v124, s[86:87]
	global_load_dwordx4 v[156:159], v124, s[66:67]
	global_load_dwordx4 v[164:167], v124, s[56:57]
	v_mul_f32_e64 v125, |v152|, s69
	v_mul_f32_e64 v129, |v153|, s69
	v_exp_f32_e32 v125, v125
	v_exp_f32_e32 v146, v129
	v_mul_f32_e64 v137, |v154|, s69
	v_max_f32_e32 v142, v154, v154
	v_cmp_lt_f32_e32 vcc, 0, v153
	v_max_f32_e32 v136, v153, v153
	v_mul_f32_e64 v143, |v155|, s69
	v_exp_f32_e32 v171, v137
	v_min_f32_e32 v124, 0, v142
	v_add_f32_e32 v142, 1.0, v125
	v_cndmask_b32_e32 v137, 1.0, v146, vcc
	v_cmp_lt_f32_e32 vcc, 0, v152
	v_min_f32_e32 v129, 0, v136
	v_exp_f32_e32 v180, v143
	v_add_f32_e32 v143, 1.0, v146
	v_cndmask_b32_e32 v136, 1.0, v125, vcc
	v_cmp_gt_f32_e32 vcc, s74, v142
	v_cmp_gt_f32_e64 s[10:11], s74, v143
	v_rcp_f32_e32 v147, v143
	v_cndmask_b32_e64 v125, 0, 32, vcc
	v_cndmask_b32_e64 v150, 0, 32, s[10:11]
	v_ldexp_f32 v125, v142, v125
	v_ldexp_f32 v143, v143, v150
	v_log_f32_e32 v125, v125
	v_log_f32_e32 v143, v143
	v_rcp_f32_e32 v146, v142
	v_cndmask_b32_e32 v142, 0, v226, vcc
	v_mul_f32_e32 v184, 0x3f317217, v125
	v_mul_f32_e32 v185, 0x3f317217, v143
	v_fma_f32 v184, v125, s75, -v184
	v_fma_f32 v185, v143, s75, -v185
	v_fmac_f32_e32 v184, 0x3377d1cf, v125
	v_fmac_f32_e32 v185, 0x3377d1cf, v143
	v_fmac_f32_e32 v184, 0x3f317217, v125
	v_cmp_lt_f32_e64 vcc, |v125|, s63
	v_add_f32_e32 v181, 1.0, v171
	v_fmac_f32_e32 v185, 0x3f317217, v143
	v_cndmask_b32_e32 v125, v125, v184, vcc
	v_cmp_lt_f32_e64 vcc, |v143|, s63
	v_max_f32_e32 v128, v152, v152
	v_cmp_gt_f32_e64 s[12:13], s74, v181
	v_cndmask_b32_e64 v150, 0, v226, s[10:11]
	v_cndmask_b32_e32 v143, v143, v185, vcc
	v_min_f32_e32 v128, 0, v128
	v_cndmask_b32_e64 v151, 0, 32, s[12:13]
	v_sub_f32_e32 v142, v125, v142
	v_sub_f32_e32 v143, v143, v150
	v_ldexp_f32 v151, v181, v151
	v_pk_add_f32 v[128:129], v[128:129], v[142:143] neg_lo:[0,1] neg_hi:[0,1]
	v_log_f32_e32 v151, v151
	v_add_f32_e32 v182, 1.0, v180
	v_cndmask_b32_e64 v183, 0, v226, s[12:13]
	s_mov_b64 s[0:1], 0
	v_mul_f32_e32 v186, 0x3f317217, v151
	v_fma_f32 v186, v151, s75, -v186
	v_fmac_f32_e32 v186, 0x3377d1cf, v151
	v_fmac_f32_e32 v186, 0x3f317217, v151
	v_cmp_lt_f32_e64 vcc, |v151|, s63
	s_waitcnt vmcnt(0)
	v_pk_add_f32 v[128:129], v[128:129], v[160:161]
	s_nop 0
	v_pk_add_f32 v[142:143], v[128:129], v[156:157] neg_lo:[0,1] neg_hi:[0,1]
	v_max_f32_e32 v125, v156, v156
	v_mul_f32_e64 v156, |v142|, s69
	v_max_f32_e32 v150, v157, v157
	v_mul_f32_e64 v157, |v143|, s69
	v_exp_f32_e32 v156, v156
	v_exp_f32_e32 v157, v157
	v_max_f32_e32 v128, v128, v125
	v_cndmask_b32_e32 v151, v151, v186, vcc
	v_add_f32_e32 v125, 1.0, v156
	v_max_f32_e32 v129, v129, v150
	v_add_f32_e32 v150, 1.0, v157
	v_cmp_gt_f32_e32 vcc, s74, v125
	v_cmp_gt_f32_e64 s[10:11], s74, v150
	s_nop 0
	v_cndmask_b32_e64 v156, 0, 32, vcc
	v_cndmask_b32_e64 v157, 0, 32, s[10:11]
	v_ldexp_f32 v125, v125, v156
	v_ldexp_f32 v150, v150, v157
	v_log_f32_e32 v125, v125
	v_log_f32_e32 v150, v150
	v_cndmask_b32_e32 v156, 0, v226, vcc
	v_cndmask_b32_e64 v157, 0, v226, s[10:11]
	v_mul_f32_e32 v160, 0x3f317217, v125
	v_mul_f32_e32 v161, 0x3f317217, v150
	v_fma_f32 v160, v125, s75, -v160
	v_fma_f32 v161, v150, s75, -v161
	v_fmac_f32_e32 v160, 0x3377d1cf, v125
	v_fmac_f32_e32 v161, 0x3377d1cf, v150
	v_fmac_f32_e32 v160, 0x3f317217, v125
	v_cmp_lt_f32_e64 vcc, |v125|, s63
	v_fmac_f32_e32 v161, 0x3f317217, v150
	s_nop 0
	v_cndmask_b32_e32 v125, v125, v160, vcc
	v_cmp_lt_f32_e64 vcc, |v150|, s63
	v_sub_f32_e32 v160, v125, v156
	s_nop 0
	v_cndmask_b32_e32 v150, v150, v161, vcc
	v_cmp_gt_f32_e32 vcc, s74, v182
	v_sub_f32_e32 v161, v150, v157
	v_sub_f32_e32 v150, v151, v183
	v_cndmask_b32_e64 v125, 0, 32, vcc
	v_ldexp_f32 v125, v182, v125
	v_log_f32_e32 v156, v125
	v_max_f32_e32 v125, v155, v155
	v_min_f32_e32 v125, 0, v125
	v_mul_f32_e32 v151, 0x3f317217, v156
	v_fma_f32 v151, v156, s75, -v151
	v_fmac_f32_e32 v151, 0x3377d1cf, v156
	v_fmac_f32_e32 v151, 0x3f317217, v156
	v_cmp_lt_f32_e64 s[10:11], |v156|, s63
	s_nop 1
	v_cndmask_b32_e64 v151, v156, v151, s[10:11]
	v_cndmask_b32_e32 v156, 0, v226, vcc
	v_sub_f32_e32 v151, v151, v156
	v_pk_add_f32 v[124:125], v[124:125], v[150:151] neg_lo:[0,1] neg_hi:[0,1]
	s_nop 0
	v_pk_add_f32 v[150:151], v[124:125], v[162:163]
	s_nop 0
	v_pk_add_f32 v[156:157], v[150:151], v[158:159] neg_lo:[0,1] neg_hi:[0,1]
	s_nop 0
	v_mul_f32_e64 v124, |v156|, s69
	v_exp_f32_e32 v162, v124
	v_pk_mul_f32 v[124:125], v[136:137], v[164:165]
	v_rcp_f32_e32 v136, v181
	v_pk_mul_f32 v[124:125], v[146:147], v[124:125]
	v_add_f32_e32 v137, 1.0, v162
	v_cmp_gt_f32_e32 vcc, s74, v137
	s_nop 1
	v_cndmask_b32_e64 v146, 0, 32, vcc
	v_ldexp_f32 v137, v137, v146
	v_log_f32_e32 v147, v137
	v_max_f32_e32 v146, v158, v158
	v_mul_f32_e64 v158, |v157|, s69
	v_exp_f32_e32 v158, v158
	v_max_f32_e32 v146, v150, v146
	v_mul_f32_e32 v150, 0x3f317217, v147
	v_fma_f32 v150, v147, s75, -v150
	v_fmac_f32_e32 v150, 0x3377d1cf, v147
	v_fmac_f32_e32 v150, 0x3f317217, v147
	v_cmp_lt_f32_e64 s[10:11], |v147|, s63
	v_add_f32_e32 v158, 1.0, v158
	v_rcp_f32_e32 v137, v182
	v_cndmask_b32_e64 v147, v147, v150, s[10:11]
	v_cndmask_b32_e32 v150, 0, v226, vcc
	v_cmp_gt_f32_e32 vcc, s74, v158
	v_sub_f32_e32 v150, v147, v150
	s_nop 0
	v_cndmask_b32_e64 v162, 0, 32, vcc
	v_ldexp_f32 v158, v158, v162
	v_log_f32_e32 v158, v158
	v_max_f32_e32 v147, v151, v159
	v_mul_f32_e32 v151, 0x3f317217, v158
	v_fma_f32 v151, v158, s75, -v151
	v_fmac_f32_e32 v151, 0x3377d1cf, v158
	v_fmac_f32_e32 v151, 0x3f317217, v158
	v_cmp_lt_f32_e64 s[10:11], |v158|, s63
	s_nop 1
	v_cndmask_b32_e64 v151, v158, v151, s[10:11]
	v_cndmask_b32_e32 v158, 0, v226, vcc
	v_cmp_lt_f32_e64 vcc, |v143|, s49
	v_sub_f32_e32 v151, v151, v158
	s_nop 0
	v_cndmask_b32_e32 v143, 0, v161, vcc
	v_cmp_lt_f32_e64 vcc, |v142|, s49
	s_nop 1
	v_cndmask_b32_e32 v142, 0, v160, vcc
	v_cmp_lt_f32_e64 vcc, |v157|, s49
	s_nop 1
	v_cndmask_b32_e32 v151, 0, v151, vcc
	v_cmp_lt_f32_e64 vcc, |v156|, s49
	v_pk_add_f32 v[156:157], v[128:129], v[142:143]
	s_nop 0
	v_cndmask_b32_e32 v150, 0, v150, vcc
	v_cmp_lt_f32_e32 vcc, 0, v155
	v_pk_add_f32 v[158:159], v[146:147], v[150:151]
	s_nop 0
	v_cndmask_b32_e32 v129, 1.0, v180, vcc
	v_cmp_lt_f32_e32 vcc, 0, v154
	s_nop 1
	v_cndmask_b32_e32 v128, 1.0, v171, vcc
	v_pk_mul_f32 v[128:129], v[128:129], v[166:167]
	s_nop 0
	v_pk_mul_f32 v[128:129], v[136:137], v[128:129]
	v_lshl_add_u64 v[136:137], v[210:211], 2, s[94:95]
	global_store_dwordx4 v[136:137], v[156:159], off

.LBB0_1226:
	s_add_u32 s0, s22, s0
	s_addc_u32 s1, s23, s1
	v_mov_b32_e32 v209, v208
	v_lshl_add_u64 v[124:125], v[124:125], 1, s[0:1]
	v_cvt_pk_bf16_f32 v128, v128, v129
	v_cvt_pk_bf16_f32 v129, v130, v131
	v_or_b32_e32 v206, v206, v168
	v_pk_mul_f32 v[142:143], v[126:127], v[208:209]
	s_mov_b64 s[0:1], -1
	s_and_b64 vcc, exec, s[14:15]
	global_store_dwordx2 v[124:125], v[128:129], off offset:16
	s_cbranch_vccz .LBB0_1228
	v_lshlrev_b32_e32 v124, 2, v194
	v_lshlrev_b32_e32 v136, 2, v168
	global_load_dwordx4 v[128:131], v124, s[86:87] offset:48
	s_nop 0
	global_load_dwordx4 v[124:127], v136, s[66:67]
	v_mul_f32_e64 v144, |v140|, s69
	global_load_dwordx4 v[136:139], v136, s[56:57]
	v_max_f32_e32 v145, v140, v140
	v_mul_f32_e64 v146, |v141|, s69
	v_exp_f32_e32 v153, v144
	v_min_f32_e32 v148, 0, v145
	v_exp_f32_e32 v145, v146
	v_max_f32_e32 v147, v141, v141
	v_mul_f32_e64 v152, |v143|, s69
	v_cmp_lt_f32_e32 vcc, 0, v141
	v_min_f32_e32 v149, 0, v147
	v_exp_f32_e32 v155, v152
	v_add_f32_e32 v152, 1.0, v153
	v_cndmask_b32_e32 v147, 1.0, v145, vcc
	v_cmp_lt_f32_e32 vcc, 0, v140
	v_add_f32_e32 v156, 1.0, v145
	v_cmp_gt_f32_e64 s[10:11], s74, v156
	v_cndmask_b32_e32 v146, 1.0, v153, vcc
	v_cmp_gt_f32_e32 vcc, s74, v152
	v_cndmask_b32_e64 v153, 0, 32, s[10:11]
	v_ldexp_f32 v153, v156, v153
	v_cndmask_b32_e64 v145, 0, 32, vcc
	v_ldexp_f32 v145, v152, v145
	v_log_f32_e32 v145, v145
	v_log_f32_e32 v153, v153
	v_mul_f32_e64 v150, |v142|, s69
	v_exp_f32_e32 v154, v150
	v_mul_f32_e32 v161, 0x3f317217, v145
	v_mul_f32_e32 v162, 0x3f317217, v153
	v_fma_f32 v161, v145, s75, -v161
	v_fma_f32 v162, v153, s75, -v162
	v_fmac_f32_e32 v161, 0x3377d1cf, v145
	v_rcp_f32_e32 v150, v152
	v_cndmask_b32_e32 v152, 0, v226, vcc
	v_fmac_f32_e32 v162, 0x3377d1cf, v153
	v_fmac_f32_e32 v161, 0x3f317217, v145
	v_cmp_lt_f32_e64 vcc, |v145|, s63
	v_max_f32_e32 v151, v142, v142
	v_add_f32_e32 v157, 1.0, v154
	v_fmac_f32_e32 v162, 0x3f317217, v153
	v_cndmask_b32_e32 v145, v145, v161, vcc
	v_cmp_lt_f32_e64 vcc, |v153|, s63
	v_min_f32_e32 v144, 0, v151
	v_rcp_f32_e32 v151, v156
	v_cmp_gt_f32_e64 s[12:13], s74, v157
	v_cndmask_b32_e64 v156, 0, v226, s[10:11]
	v_cndmask_b32_e32 v153, v153, v162, vcc
	v_cndmask_b32_e64 v159, 0, 32, s[12:13]
	v_sub_f32_e32 v152, v145, v152
	v_sub_f32_e32 v153, v153, v156
	v_ldexp_f32 v159, v157, v159
	v_pk_add_f32 v[148:149], v[148:149], v[152:153] neg_lo:[0,1] neg_hi:[0,1]
	v_log_f32_e32 v159, v159
	v_add_f32_e32 v158, 1.0, v155
	v_cndmask_b32_e64 v160, 0, v226, s[12:13]
	s_mov_b64 s[0:1], 0
	v_mul_f32_e32 v163, 0x3f317217, v159
	v_fma_f32 v163, v159, s75, -v163
	v_fmac_f32_e32 v163, 0x3377d1cf, v159
	v_fmac_f32_e32 v163, 0x3f317217, v159
	v_cmp_lt_f32_e64 vcc, |v159|, s63
	s_waitcnt vmcnt(0)
	v_pk_add_f32 v[148:149], v[148:149], v[128:129]
	s_nop 0
	v_pk_add_f32 v[128:129], v[148:149], v[124:125] neg_lo:[0,1] neg_hi:[0,1]
	v_max_f32_e32 v145, v124, v124
	v_mul_f32_e64 v124, |v128|, s69
	v_max_f32_e32 v152, v125, v125
	v_mul_f32_e64 v125, |v129|, s69
	v_exp_f32_e32 v153, v124
	v_exp_f32_e32 v156, v125
	v_max_f32_e32 v124, v148, v145
	v_cndmask_b32_e32 v159, v159, v163, vcc
	v_add_f32_e32 v145, 1.0, v153
	v_add_f32_e32 v148, 1.0, v156
	v_cmp_gt_f32_e32 vcc, s74, v145
	v_max_f32_e32 v125, v149, v152
	v_cmp_gt_f32_e64 s[10:11], s74, v148
	v_cndmask_b32_e64 v149, 0, 32, vcc
	v_ldexp_f32 v145, v145, v149
	v_cndmask_b32_e64 v152, 0, 32, s[10:11]
	v_ldexp_f32 v148, v148, v152
	v_log_f32_e32 v145, v145
	v_log_f32_e32 v148, v148
	v_cndmask_b32_e32 v149, 0, v226, vcc
	v_cndmask_b32_e64 v152, 0, v226, s[10:11]
	v_mul_f32_e32 v153, 0x3f317217, v145
	v_mul_f32_e32 v156, 0x3f317217, v148
	v_fma_f32 v153, v145, s75, -v153
	v_fma_f32 v156, v148, s75, -v156
	v_fmac_f32_e32 v153, 0x3377d1cf, v145
	v_fmac_f32_e32 v156, 0x3377d1cf, v148
	v_fmac_f32_e32 v153, 0x3f317217, v145
	v_cmp_lt_f32_e64 vcc, |v145|, s63
	v_fmac_f32_e32 v156, 0x3f317217, v148
	v_pk_mul_f32 v[136:137], v[146:147], v[136:137]
	v_cndmask_b32_e32 v145, v145, v153, vcc
	v_cmp_lt_f32_e64 vcc, |v148|, s63
	v_sub_f32_e32 v153, v145, v149
	v_pk_mul_f32 v[136:137], v[150:151], v[136:137]
	v_cndmask_b32_e32 v148, v148, v156, vcc
	v_cmp_gt_f32_e32 vcc, s74, v158
	v_sub_f32_e32 v152, v148, v152
	v_sub_f32_e32 v148, v159, v160
	v_cndmask_b32_e64 v145, 0, 32, vcc
	v_ldexp_f32 v145, v158, v145
	v_log_f32_e32 v149, v145
	v_max_f32_e32 v145, v143, v143
	v_min_f32_e32 v145, 0, v145
	v_rcp_f32_e32 v146, v157
	v_mul_f32_e32 v156, 0x3f317217, v149
	v_fma_f32 v156, v149, s75, -v156
	v_fmac_f32_e32 v156, 0x3377d1cf, v149
	v_fmac_f32_e32 v156, 0x3f317217, v149
	v_cmp_lt_f32_e64 s[10:11], |v149|, s63
	s_nop 1
	v_cndmask_b32_e64 v149, v149, v156, s[10:11]
	v_cndmask_b32_e32 v156, 0, v226, vcc
	v_sub_f32_e32 v149, v149, v156
	v_pk_add_f32 v[144:145], v[144:145], v[148:149] neg_lo:[0,1] neg_hi:[0,1]
	s_nop 0
	v_pk_add_f32 v[130:131], v[144:145], v[130:131]
	s_nop 0
	v_pk_add_f32 v[144:145], v[130:131], v[126:127] neg_lo:[0,1] neg_hi:[0,1]
	v_mul_f32_e64 v148, |v144|, s69
	v_exp_f32_e32 v148, v148
	v_mul_f32_e64 v149, |v145|, s69
	v_exp_f32_e32 v149, v149
	v_max_f32_e32 v126, v130, v126
	v_add_f32_e32 v147, 1.0, v148
	v_cmp_gt_f32_e32 vcc, s74, v147
	v_add_f32_e32 v149, 1.0, v149
	s_nop 0
	v_cndmask_b32_e64 v148, 0, 32, vcc
	v_ldexp_f32 v147, v147, v148
	v_log_f32_e32 v148, v147
	v_max_f32_e32 v127, v131, v127
	v_rcp_f32_e32 v147, v158
	v_mul_f32_e32 v130, 0x3f317217, v148
	v_fma_f32 v130, v148, s75, -v130
	v_fmac_f32_e32 v130, 0x3377d1cf, v148
	v_fmac_f32_e32 v130, 0x3f317217, v148
	v_cmp_lt_f32_e64 s[10:11], |v148|, s63
	s_nop 1
	v_cndmask_b32_e64 v130, v148, v130, s[10:11]
	v_cndmask_b32_e32 v148, 0, v226, vcc
	v_cmp_gt_f32_e32 vcc, s74, v149
	v_sub_f32_e32 v130, v130, v148
	s_nop 0
	v_cndmask_b32_e64 v150, 0, 32, vcc
	v_ldexp_f32 v149, v149, v150
	v_log_f32_e32 v149, v149
	v_cndmask_b32_e32 v148, 0, v226, vcc
	v_cmp_lt_f32_e64 vcc, |v129|, s49
	v_mul_f32_e32 v131, 0x3f317217, v149
	v_fma_f32 v131, v149, s75, -v131
	v_fmac_f32_e32 v131, 0x3377d1cf, v149
	v_fmac_f32_e32 v131, 0x3f317217, v149
	v_cmp_lt_f32_e64 s[10:11], |v149|, s63
	v_cndmask_b32_e32 v129, 0, v152, vcc
	v_cmp_lt_f32_e64 vcc, |v128|, s49
	v_cndmask_b32_e64 v131, v149, v131, s[10:11]
	v_sub_f32_e32 v131, v131, v148
	v_cndmask_b32_e32 v128, 0, v153, vcc
	v_cmp_lt_f32_e64 vcc, |v145|, s49
	v_pk_add_f32 v[124:125], v[124:125], v[128:129]
	s_nop 0
	v_cndmask_b32_e32 v131, 0, v131, vcc
	v_cmp_lt_f32_e64 vcc, |v144|, s49
	s_nop 1
	v_cndmask_b32_e32 v130, 0, v130, vcc
	v_cmp_lt_f32_e32 vcc, 0, v143
	v_pk_add_f32 v[126:127], v[126:127], v[130:131]
	v_lshl_add_u64 v[130:131], v[206:207], 2, s[94:95]
	v_cndmask_b32_e32 v129, 1.0, v155, vcc
	v_cmp_lt_f32_e32 vcc, 0, v142
	global_store_dwordx4 v[130:131], v[124:127], off
	s_nop 0
	v_cndmask_b32_e32 v128, 1.0, v154, vcc
	v_pk_mul_f32 v[128:129], v[128:129], v[138:139]
	v_lshl_add_u64 v[124:125], v[206:207], 1, s[84:85]
	v_pk_mul_f32 v[128:129], v[146:147], v[128:129]
	v_cvt_pk_bf16_f32 v126, v136, v137
	v_cvt_pk_bf16_f32 v127, v128, v129
	global_store_dwordx2 v[124:125], v[126:127], off

.LBB0_1249:
	v_cndmask_b32_e64 v104, 0, 1, s[14:15]
	s_and_b64 vcc, exec, s[0:1]
	v_cmp_ne_u32_e64 s[10:11], 1, v104
	s_cbranch_vccz .LBB0_1266
	s_and_b64 vcc, exec, s[10:11]
	s_mov_b64 s[0:1], -1
	s_cbranch_vccnz .LBB0_1252
	v_lshlrev_b32_e32 v104, 2, v194
	global_load_dwordx4 v[140:143], v104, s[86:87]
	global_load_dwordx4 v[136:139], v104, s[66:67]
	global_load_dwordx4 v[144:147], v104, s[56:57]
	v_mul_f32_e64 v105, |v132|, s69
	v_mul_f32_e64 v109, |v133|, s69
	v_exp_f32_e32 v105, v105
	v_exp_f32_e32 v126, v109
	v_mul_f32_e64 v113, |v134|, s69
	v_max_f32_e32 v122, v134, v134
	v_cmp_lt_f32_e32 vcc, 0, v133
	v_max_f32_e32 v112, v133, v133
	v_mul_f32_e64 v123, |v135|, s69
	v_exp_f32_e32 v148, v113
	v_min_f32_e32 v104, 0, v122
	v_add_f32_e32 v122, 1.0, v105
	v_cndmask_b32_e32 v113, 1.0, v126, vcc
	v_cmp_lt_f32_e32 vcc, 0, v132
	v_min_f32_e32 v109, 0, v112
	v_exp_f32_e32 v149, v123
	v_add_f32_e32 v123, 1.0, v126
	v_cndmask_b32_e32 v112, 1.0, v105, vcc
	v_cmp_gt_f32_e32 vcc, s74, v122
	v_cmp_gt_f32_e64 s[14:15], s74, v123
	v_rcp_f32_e32 v127, v123
	v_cndmask_b32_e64 v105, 0, 32, vcc
	v_cndmask_b32_e64 v130, 0, 32, s[14:15]
	v_ldexp_f32 v105, v122, v105
	v_ldexp_f32 v123, v123, v130
	v_log_f32_e32 v105, v105
	v_log_f32_e32 v123, v123
	v_rcp_f32_e32 v126, v122
	v_cndmask_b32_e32 v122, 0, v226, vcc
	v_mul_f32_e32 v158, 0x3f317217, v105
	v_mul_f32_e32 v159, 0x3f317217, v123
	v_fma_f32 v158, v105, s75, -v158
	v_fma_f32 v159, v123, s75, -v159
	v_fmac_f32_e32 v158, 0x3377d1cf, v105
	v_fmac_f32_e32 v159, 0x3377d1cf, v123
	v_fmac_f32_e32 v158, 0x3f317217, v105
	v_cmp_lt_f32_e64 vcc, |v105|, s63
	v_add_f32_e32 v150, 1.0, v148
	v_fmac_f32_e32 v159, 0x3f317217, v123
	v_cndmask_b32_e32 v105, v105, v158, vcc
	v_cmp_lt_f32_e64 vcc, |v123|, s63
	v_max_f32_e32 v108, v132, v132
	v_cmp_gt_f32_e64 s[16:17], s74, v150
	v_cndmask_b32_e64 v130, 0, v226, s[14:15]
	v_cndmask_b32_e32 v123, v123, v159, vcc
	v_min_f32_e32 v108, 0, v108
	v_cndmask_b32_e64 v131, 0, 32, s[16:17]
	v_sub_f32_e32 v122, v105, v122
	v_sub_f32_e32 v123, v123, v130
	v_ldexp_f32 v131, v150, v131
	v_pk_add_f32 v[108:109], v[108:109], v[122:123] neg_lo:[0,1] neg_hi:[0,1]
	v_log_f32_e32 v131, v131
	v_add_f32_e32 v151, 1.0, v149
	v_cndmask_b32_e64 v155, 0, v226, s[16:17]
	s_mov_b64 s[0:1], 0
	v_mul_f32_e32 v160, 0x3f317217, v131
	v_fma_f32 v160, v131, s75, -v160
	v_fmac_f32_e32 v160, 0x3377d1cf, v131
	v_fmac_f32_e32 v160, 0x3f317217, v131
	v_cmp_lt_f32_e64 vcc, |v131|, s63
	s_waitcnt vmcnt(0)
	v_pk_add_f32 v[108:109], v[108:109], v[140:141]
	s_nop 0
	v_pk_add_f32 v[122:123], v[108:109], v[136:137] neg_lo:[0,1] neg_hi:[0,1]
	v_max_f32_e32 v105, v136, v136
	v_mul_f32_e64 v136, |v122|, s69
	v_max_f32_e32 v130, v137, v137
	v_mul_f32_e64 v137, |v123|, s69
	v_exp_f32_e32 v136, v136
	v_exp_f32_e32 v137, v137
	v_max_f32_e32 v108, v108, v105
	v_cndmask_b32_e32 v131, v131, v160, vcc
	v_add_f32_e32 v105, 1.0, v136
	v_max_f32_e32 v109, v109, v130
	v_add_f32_e32 v130, 1.0, v137
	v_cmp_gt_f32_e32 vcc, s74, v105
	v_cmp_gt_f32_e64 s[14:15], s74, v130
	s_nop 0
	v_cndmask_b32_e64 v136, 0, 32, vcc
	v_cndmask_b32_e64 v137, 0, 32, s[14:15]
	v_ldexp_f32 v105, v105, v136
	v_ldexp_f32 v130, v130, v137
	v_log_f32_e32 v105, v105
	v_log_f32_e32 v130, v130
	v_cndmask_b32_e32 v136, 0, v226, vcc
	v_cndmask_b32_e64 v137, 0, v226, s[14:15]
	v_mul_f32_e32 v140, 0x3f317217, v105
	v_mul_f32_e32 v141, 0x3f317217, v130
	v_fma_f32 v140, v105, s75, -v140
	v_fma_f32 v141, v130, s75, -v141
	v_fmac_f32_e32 v140, 0x3377d1cf, v105
	v_fmac_f32_e32 v141, 0x3377d1cf, v130
	v_fmac_f32_e32 v140, 0x3f317217, v105
	v_cmp_lt_f32_e64 vcc, |v105|, s63
	v_fmac_f32_e32 v141, 0x3f317217, v130
	s_nop 0
	v_cndmask_b32_e32 v105, v105, v140, vcc
	v_cmp_lt_f32_e64 vcc, |v130|, s63
	v_sub_f32_e32 v140, v105, v136
	s_nop 0
	v_cndmask_b32_e32 v130, v130, v141, vcc
	v_cmp_gt_f32_e32 vcc, s74, v151
	v_sub_f32_e32 v141, v130, v137
	v_sub_f32_e32 v130, v131, v155
	v_cndmask_b32_e64 v105, 0, 32, vcc
	v_ldexp_f32 v105, v151, v105
	v_log_f32_e32 v136, v105
	v_max_f32_e32 v105, v135, v135
	v_min_f32_e32 v105, 0, v105
	v_mul_f32_e32 v131, 0x3f317217, v136
	v_fma_f32 v131, v136, s75, -v131
	v_fmac_f32_e32 v131, 0x3377d1cf, v136
	v_fmac_f32_e32 v131, 0x3f317217, v136
	v_cmp_lt_f32_e64 s[14:15], |v136|, s63
	s_nop 1
	v_cndmask_b32_e64 v131, v136, v131, s[14:15]
	v_cndmask_b32_e32 v136, 0, v226, vcc
	v_sub_f32_e32 v131, v131, v136
	v_pk_add_f32 v[104:105], v[104:105], v[130:131] neg_lo:[0,1] neg_hi:[0,1]
	s_nop 0
	v_pk_add_f32 v[130:131], v[104:105], v[142:143]
	s_nop 0
	v_pk_add_f32 v[136:137], v[130:131], v[138:139] neg_lo:[0,1] neg_hi:[0,1]
	s_nop 0
	v_mul_f32_e64 v104, |v136|, s69
	v_exp_f32_e32 v142, v104
	v_pk_mul_f32 v[104:105], v[112:113], v[144:145]
	v_rcp_f32_e32 v112, v150
	v_pk_mul_f32 v[104:105], v[126:127], v[104:105]
	v_add_f32_e32 v113, 1.0, v142
	v_cmp_gt_f32_e32 vcc, s74, v113
	s_nop 1
	v_cndmask_b32_e64 v126, 0, 32, vcc
	v_ldexp_f32 v113, v113, v126
	v_log_f32_e32 v127, v113
	v_max_f32_e32 v126, v138, v138
	v_mul_f32_e64 v138, |v137|, s69
	v_exp_f32_e32 v138, v138
	v_max_f32_e32 v126, v130, v126
	v_mul_f32_e32 v130, 0x3f317217, v127
	v_fma_f32 v130, v127, s75, -v130
	v_fmac_f32_e32 v130, 0x3377d1cf, v127
	v_fmac_f32_e32 v130, 0x3f317217, v127
	v_cmp_lt_f32_e64 s[14:15], |v127|, s63
	v_add_f32_e32 v138, 1.0, v138
	v_rcp_f32_e32 v113, v151
	v_cndmask_b32_e64 v127, v127, v130, s[14:15]
	v_cndmask_b32_e32 v130, 0, v226, vcc
	v_cmp_gt_f32_e32 vcc, s74, v138
	v_sub_f32_e32 v130, v127, v130
	s_nop 0
	v_cndmask_b32_e64 v142, 0, 32, vcc
	v_ldexp_f32 v138, v138, v142
	v_log_f32_e32 v138, v138
	v_max_f32_e32 v127, v131, v139
	v_mul_f32_e32 v131, 0x3f317217, v138
	v_fma_f32 v131, v138, s75, -v131
	v_fmac_f32_e32 v131, 0x3377d1cf, v138
	v_fmac_f32_e32 v131, 0x3f317217, v138
	v_cmp_lt_f32_e64 s[14:15], |v138|, s63
	s_nop 1
	v_cndmask_b32_e64 v131, v138, v131, s[14:15]
	v_cndmask_b32_e32 v138, 0, v226, vcc
	v_cmp_lt_f32_e64 vcc, |v123|, s49
	v_sub_f32_e32 v131, v131, v138
	s_nop 0
	v_cndmask_b32_e32 v123, 0, v141, vcc
	v_cmp_lt_f32_e64 vcc, |v122|, s49
	s_nop 1
	v_cndmask_b32_e32 v122, 0, v140, vcc
	v_cmp_lt_f32_e64 vcc, |v137|, s49
	s_nop 1
	v_cndmask_b32_e32 v131, 0, v131, vcc
	v_cmp_lt_f32_e64 vcc, |v136|, s49
	v_pk_add_f32 v[136:137], v[108:109], v[122:123]
	s_nop 0
	v_cndmask_b32_e32 v130, 0, v130, vcc
	v_cmp_lt_f32_e32 vcc, 0, v135
	v_pk_add_f32 v[138:139], v[126:127], v[130:131]
	s_nop 0
	v_cndmask_b32_e32 v109, 1.0, v149, vcc
	v_cmp_lt_f32_e32 vcc, 0, v134
	s_nop 1
	v_cndmask_b32_e32 v108, 1.0, v148, vcc
	v_pk_mul_f32 v[108:109], v[108:109], v[146:147]
	s_nop 0
	v_pk_mul_f32 v[108:109], v[112:113], v[108:109]
	v_lshl_add_u64 v[112:113], v[156:157], 2, s[94:95]
	global_store_dwordx4 v[112:113], v[136:139], off

.LBB0_1262:
	s_add_u32 s0, s22, s0
	s_addc_u32 s1, s23, s1
	v_mov_b32_e32 v155, v154
	v_lshl_add_u64 v[104:105], v[104:105], 1, s[0:1]
	v_cvt_pk_bf16_f32 v108, v108, v109
	v_cvt_pk_bf16_f32 v109, v110, v111
	v_or_b32_e32 v152, v152, v168
	v_pk_mul_f32 v[122:123], v[106:107], v[154:155]
	s_and_b64 vcc, exec, s[10:11]
	s_mov_b64 s[0:1], -1
	global_store_dwordx2 v[104:105], v[108:109], off offset:16
	s_cbranch_vccnz .LBB0_1264
	v_lshlrev_b32_e32 v104, 2, v194
	v_lshlrev_b32_e32 v112, 2, v168
	global_load_dwordx4 v[108:111], v104, s[86:87] offset:48
	s_nop 0
	global_load_dwordx4 v[104:107], v112, s[66:67]
	v_mul_f32_e64 v124, |v120|, s69
	global_load_dwordx4 v[112:115], v112, s[56:57]
	v_max_f32_e32 v125, v120, v120
	v_mul_f32_e64 v126, |v121|, s69
	v_exp_f32_e32 v133, v124
	v_min_f32_e32 v128, 0, v125
	v_exp_f32_e32 v125, v126
	v_max_f32_e32 v127, v121, v121
	v_mul_f32_e64 v132, |v123|, s69
	v_cmp_lt_f32_e32 vcc, 0, v121
	v_min_f32_e32 v129, 0, v127
	v_exp_f32_e32 v135, v132
	v_add_f32_e32 v132, 1.0, v133
	v_cndmask_b32_e32 v127, 1.0, v125, vcc
	v_cmp_lt_f32_e32 vcc, 0, v120
	v_add_f32_e32 v136, 1.0, v125
	v_cmp_gt_f32_e64 s[14:15], s74, v136
	v_cndmask_b32_e32 v126, 1.0, v133, vcc
	v_cmp_gt_f32_e32 vcc, s74, v132
	v_cndmask_b32_e64 v133, 0, 32, s[14:15]
	v_ldexp_f32 v133, v136, v133
	v_cndmask_b32_e64 v125, 0, 32, vcc
	v_ldexp_f32 v125, v132, v125
	v_log_f32_e32 v125, v125
	v_log_f32_e32 v133, v133
	v_mul_f32_e64 v130, |v122|, s69
	v_exp_f32_e32 v134, v130
	v_mul_f32_e32 v141, 0x3f317217, v125
	v_mul_f32_e32 v142, 0x3f317217, v133
	v_fma_f32 v141, v125, s75, -v141
	v_fma_f32 v142, v133, s75, -v142
	v_fmac_f32_e32 v141, 0x3377d1cf, v125
	v_rcp_f32_e32 v130, v132
	v_cndmask_b32_e32 v132, 0, v226, vcc
	v_fmac_f32_e32 v142, 0x3377d1cf, v133
	v_fmac_f32_e32 v141, 0x3f317217, v125
	v_cmp_lt_f32_e64 vcc, |v125|, s63
	v_max_f32_e32 v131, v122, v122
	v_add_f32_e32 v137, 1.0, v134
	v_fmac_f32_e32 v142, 0x3f317217, v133
	v_cndmask_b32_e32 v125, v125, v141, vcc
	v_cmp_lt_f32_e64 vcc, |v133|, s63
	v_min_f32_e32 v124, 0, v131
	v_rcp_f32_e32 v131, v136
	v_cmp_gt_f32_e64 s[16:17], s74, v137
	v_cndmask_b32_e64 v136, 0, v226, s[14:15]
	v_cndmask_b32_e32 v133, v133, v142, vcc
	v_cndmask_b32_e64 v139, 0, 32, s[16:17]
	v_sub_f32_e32 v132, v125, v132
	v_sub_f32_e32 v133, v133, v136
	v_ldexp_f32 v139, v137, v139
	v_pk_add_f32 v[128:129], v[128:129], v[132:133] neg_lo:[0,1] neg_hi:[0,1]
	v_log_f32_e32 v139, v139
	v_add_f32_e32 v138, 1.0, v135
	v_cndmask_b32_e64 v140, 0, v226, s[16:17]
	s_mov_b64 s[0:1], 0
	v_mul_f32_e32 v143, 0x3f317217, v139
	v_fma_f32 v143, v139, s75, -v143
	v_fmac_f32_e32 v143, 0x3377d1cf, v139
	v_fmac_f32_e32 v143, 0x3f317217, v139
	v_cmp_lt_f32_e64 vcc, |v139|, s63
	s_waitcnt vmcnt(0)
	v_pk_add_f32 v[128:129], v[128:129], v[108:109]
	s_nop 0
	v_pk_add_f32 v[108:109], v[128:129], v[104:105] neg_lo:[0,1] neg_hi:[0,1]
	v_max_f32_e32 v125, v104, v104
	v_mul_f32_e64 v104, |v108|, s69
	v_max_f32_e32 v132, v105, v105
	v_mul_f32_e64 v105, |v109|, s69
	v_exp_f32_e32 v133, v104
	v_exp_f32_e32 v136, v105
	v_max_f32_e32 v104, v128, v125
	v_cndmask_b32_e32 v139, v139, v143, vcc
	v_add_f32_e32 v125, 1.0, v133
	v_add_f32_e32 v128, 1.0, v136
	v_cmp_gt_f32_e32 vcc, s74, v125
	v_max_f32_e32 v105, v129, v132
	v_cmp_gt_f32_e64 s[14:15], s74, v128
	v_cndmask_b32_e64 v129, 0, 32, vcc
	v_ldexp_f32 v125, v125, v129
	v_cndmask_b32_e64 v132, 0, 32, s[14:15]
	v_ldexp_f32 v128, v128, v132
	v_log_f32_e32 v125, v125
	v_log_f32_e32 v128, v128
	v_cndmask_b32_e32 v129, 0, v226, vcc
	v_cndmask_b32_e64 v132, 0, v226, s[14:15]
	v_mul_f32_e32 v133, 0x3f317217, v125
	v_mul_f32_e32 v136, 0x3f317217, v128
	v_fma_f32 v133, v125, s75, -v133
	v_fma_f32 v136, v128, s75, -v136
	v_fmac_f32_e32 v133, 0x3377d1cf, v125
	v_fmac_f32_e32 v136, 0x3377d1cf, v128
	v_fmac_f32_e32 v133, 0x3f317217, v125
	v_cmp_lt_f32_e64 vcc, |v125|, s63
	v_fmac_f32_e32 v136, 0x3f317217, v128
	v_pk_mul_f32 v[112:113], v[126:127], v[112:113]
	v_cndmask_b32_e32 v125, v125, v133, vcc
	v_cmp_lt_f32_e64 vcc, |v128|, s63
	v_sub_f32_e32 v133, v125, v129
	v_pk_mul_f32 v[112:113], v[130:131], v[112:113]
	v_cndmask_b32_e32 v128, v128, v136, vcc
	v_cmp_gt_f32_e32 vcc, s74, v138
	v_sub_f32_e32 v132, v128, v132
	v_sub_f32_e32 v128, v139, v140
	v_cndmask_b32_e64 v125, 0, 32, vcc
	v_ldexp_f32 v125, v138, v125
	v_log_f32_e32 v129, v125
	v_max_f32_e32 v125, v123, v123
	v_min_f32_e32 v125, 0, v125
	v_rcp_f32_e32 v126, v137
	v_mul_f32_e32 v136, 0x3f317217, v129
	v_fma_f32 v136, v129, s75, -v136
	v_fmac_f32_e32 v136, 0x3377d1cf, v129
	v_fmac_f32_e32 v136, 0x3f317217, v129
	v_cmp_lt_f32_e64 s[14:15], |v129|, s63
	s_nop 1
	v_cndmask_b32_e64 v129, v129, v136, s[14:15]
	v_cndmask_b32_e32 v136, 0, v226, vcc
	v_sub_f32_e32 v129, v129, v136
	v_pk_add_f32 v[124:125], v[124:125], v[128:129] neg_lo:[0,1] neg_hi:[0,1]
	s_nop 0
	v_pk_add_f32 v[110:111], v[124:125], v[110:111]
	s_nop 0
	v_pk_add_f32 v[124:125], v[110:111], v[106:107] neg_lo:[0,1] neg_hi:[0,1]
	v_mul_f32_e64 v128, |v124|, s69
	v_exp_f32_e32 v128, v128
	v_mul_f32_e64 v129, |v125|, s69
	v_exp_f32_e32 v129, v129
	v_max_f32_e32 v106, v110, v106
	v_add_f32_e32 v127, 1.0, v128
	v_cmp_gt_f32_e32 vcc, s74, v127
	v_add_f32_e32 v129, 1.0, v129
	s_nop 0
	v_cndmask_b32_e64 v128, 0, 32, vcc
	v_ldexp_f32 v127, v127, v128
	v_log_f32_e32 v128, v127
	v_max_f32_e32 v107, v111, v107
	v_rcp_f32_e32 v127, v138
	v_mul_f32_e32 v110, 0x3f317217, v128
	v_fma_f32 v110, v128, s75, -v110
	v_fmac_f32_e32 v110, 0x3377d1cf, v128
	v_fmac_f32_e32 v110, 0x3f317217, v128
	v_cmp_lt_f32_e64 s[14:15], |v128|, s63
	s_nop 1
	v_cndmask_b32_e64 v110, v128, v110, s[14:15]
	v_cndmask_b32_e32 v128, 0, v226, vcc
	v_cmp_gt_f32_e32 vcc, s74, v129
	v_sub_f32_e32 v110, v110, v128
	s_nop 0
	v_cndmask_b32_e64 v130, 0, 32, vcc
	v_ldexp_f32 v129, v129, v130
	v_log_f32_e32 v129, v129
	v_cndmask_b32_e32 v128, 0, v226, vcc
	v_cmp_lt_f32_e64 vcc, |v109|, s49
	v_mul_f32_e32 v111, 0x3f317217, v129
	v_fma_f32 v111, v129, s75, -v111
	v_fmac_f32_e32 v111, 0x3377d1cf, v129
	v_fmac_f32_e32 v111, 0x3f317217, v129
	v_cmp_lt_f32_e64 s[14:15], |v129|, s63
	v_cndmask_b32_e32 v109, 0, v132, vcc
	v_cmp_lt_f32_e64 vcc, |v108|, s49
	v_cndmask_b32_e64 v111, v129, v111, s[14:15]
	v_sub_f32_e32 v111, v111, v128
	v_cndmask_b32_e32 v108, 0, v133, vcc
	v_cmp_lt_f32_e64 vcc, |v125|, s49
	v_pk_add_f32 v[104:105], v[104:105], v[108:109]
	s_nop 0
	v_cndmask_b32_e32 v111, 0, v111, vcc
	v_cmp_lt_f32_e64 vcc, |v124|, s49
	s_nop 1
	v_cndmask_b32_e32 v110, 0, v110, vcc
	v_cmp_lt_f32_e32 vcc, 0, v123
	v_pk_add_f32 v[106:107], v[106:107], v[110:111]
	v_lshl_add_u64 v[110:111], v[152:153], 2, s[94:95]
	v_cndmask_b32_e32 v109, 1.0, v135, vcc
	v_cmp_lt_f32_e32 vcc, 0, v122
	global_store_dwordx4 v[110:111], v[104:107], off
	s_nop 0
	v_cndmask_b32_e32 v108, 1.0, v134, vcc
	v_pk_mul_f32 v[108:109], v[108:109], v[114:115]
	v_lshl_add_u64 v[104:105], v[152:153], 1, s[84:85]
	v_pk_mul_f32 v[108:109], v[126:127], v[108:109]
	v_cvt_pk_bf16_f32 v106, v112, v113
	v_cvt_pk_bf16_f32 v107, v108, v109
	global_store_dwordx2 v[104:105], v[106:107], off

.LBB0_1285:
	s_and_b64 vcc, exec, s[0:1]
	s_cbranch_vccz .LBB0_1302
	s_and_b64 vcc, exec, s[10:11]
	s_mov_b64 s[0:1], -1
	s_cbranch_vccnz .LBB0_1288
	v_lshlrev_b32_e32 v84, 2, v194
	global_load_dwordx4 v[120:123], v84, s[86:87]
	global_load_dwordx4 v[116:119], v84, s[66:67]
	global_load_dwordx4 v[124:127], v84, s[56:57]
	v_mul_f32_e64 v85, |v112|, s69
	v_mul_f32_e64 v89, |v113|, s69
	v_exp_f32_e32 v85, v85
	v_exp_f32_e32 v106, v89
	v_mul_f32_e64 v93, |v114|, s69
	v_max_f32_e32 v102, v114, v114
	v_cmp_lt_f32_e32 vcc, 0, v113
	v_max_f32_e32 v92, v113, v113
	v_mul_f32_e64 v103, |v115|, s69
	v_exp_f32_e32 v128, v93
	v_min_f32_e32 v84, 0, v102
	v_add_f32_e32 v102, 1.0, v85
	v_cndmask_b32_e32 v93, 1.0, v106, vcc
	v_cmp_lt_f32_e32 vcc, 0, v112
	v_min_f32_e32 v89, 0, v92
	v_exp_f32_e32 v129, v103
	v_add_f32_e32 v103, 1.0, v106
	v_cndmask_b32_e32 v92, 1.0, v85, vcc
	v_cmp_gt_f32_e32 vcc, s74, v102
	v_cmp_gt_f32_e64 s[14:15], s74, v103
	v_rcp_f32_e32 v107, v103
	v_cndmask_b32_e64 v85, 0, 32, vcc
	v_cndmask_b32_e64 v110, 0, 32, s[14:15]
	v_ldexp_f32 v85, v102, v85
	v_ldexp_f32 v103, v103, v110
	v_log_f32_e32 v85, v85
	v_log_f32_e32 v103, v103
	v_rcp_f32_e32 v106, v102
	v_cndmask_b32_e32 v102, 0, v226, vcc
	v_mul_f32_e32 v138, 0x3f317217, v85
	v_mul_f32_e32 v139, 0x3f317217, v103
	v_fma_f32 v138, v85, s75, -v138
	v_fma_f32 v139, v103, s75, -v139
	v_fmac_f32_e32 v138, 0x3377d1cf, v85
	v_fmac_f32_e32 v139, 0x3377d1cf, v103
	v_fmac_f32_e32 v138, 0x3f317217, v85
	v_cmp_lt_f32_e64 vcc, |v85|, s63
	v_add_f32_e32 v130, 1.0, v128
	v_fmac_f32_e32 v139, 0x3f317217, v103
	v_cndmask_b32_e32 v85, v85, v138, vcc
	v_cmp_lt_f32_e64 vcc, |v103|, s63
	v_max_f32_e32 v88, v112, v112
	v_cmp_gt_f32_e64 s[16:17], s74, v130
	v_cndmask_b32_e64 v110, 0, v226, s[14:15]
	v_cndmask_b32_e32 v103, v103, v139, vcc
	v_min_f32_e32 v88, 0, v88
	v_cndmask_b32_e64 v111, 0, 32, s[16:17]
	v_sub_f32_e32 v102, v85, v102
	v_sub_f32_e32 v103, v103, v110
	v_ldexp_f32 v111, v130, v111
	v_pk_add_f32 v[88:89], v[88:89], v[102:103] neg_lo:[0,1] neg_hi:[0,1]
	v_log_f32_e32 v111, v111
	v_add_f32_e32 v131, 1.0, v129
	v_cndmask_b32_e64 v135, 0, v226, s[16:17]
	s_mov_b64 s[0:1], 0
	v_mul_f32_e32 v140, 0x3f317217, v111
	v_fma_f32 v140, v111, s75, -v140
	v_fmac_f32_e32 v140, 0x3377d1cf, v111
	v_fmac_f32_e32 v140, 0x3f317217, v111
	v_cmp_lt_f32_e64 vcc, |v111|, s63
	s_waitcnt vmcnt(0)
	v_pk_add_f32 v[88:89], v[88:89], v[120:121]
	s_nop 0
	v_pk_add_f32 v[102:103], v[88:89], v[116:117] neg_lo:[0,1] neg_hi:[0,1]
	v_max_f32_e32 v85, v116, v116
	v_mul_f32_e64 v116, |v102|, s69
	v_max_f32_e32 v110, v117, v117
	v_mul_f32_e64 v117, |v103|, s69
	v_exp_f32_e32 v116, v116
	v_exp_f32_e32 v117, v117
	v_max_f32_e32 v88, v88, v85
	v_cndmask_b32_e32 v111, v111, v140, vcc
	v_add_f32_e32 v85, 1.0, v116
	v_max_f32_e32 v89, v89, v110
	v_add_f32_e32 v110, 1.0, v117
	v_cmp_gt_f32_e32 vcc, s74, v85
	v_cmp_gt_f32_e64 s[14:15], s74, v110
	s_nop 0
	v_cndmask_b32_e64 v116, 0, 32, vcc
	v_cndmask_b32_e64 v117, 0, 32, s[14:15]
	v_ldexp_f32 v85, v85, v116
	v_ldexp_f32 v110, v110, v117
	v_log_f32_e32 v85, v85
	v_log_f32_e32 v110, v110
	v_cndmask_b32_e32 v116, 0, v226, vcc
	v_cndmask_b32_e64 v117, 0, v226, s[14:15]
	v_mul_f32_e32 v120, 0x3f317217, v85
	v_mul_f32_e32 v121, 0x3f317217, v110
	v_fma_f32 v120, v85, s75, -v120
	v_fma_f32 v121, v110, s75, -v121
	v_fmac_f32_e32 v120, 0x3377d1cf, v85
	v_fmac_f32_e32 v121, 0x3377d1cf, v110
	v_fmac_f32_e32 v120, 0x3f317217, v85
	v_cmp_lt_f32_e64 vcc, |v85|, s63
	v_fmac_f32_e32 v121, 0x3f317217, v110
	s_nop 0
	v_cndmask_b32_e32 v85, v85, v120, vcc
	v_cmp_lt_f32_e64 vcc, |v110|, s63
	v_sub_f32_e32 v120, v85, v116
	s_nop 0
	v_cndmask_b32_e32 v110, v110, v121, vcc
	v_cmp_gt_f32_e32 vcc, s74, v131
	v_sub_f32_e32 v121, v110, v117
	v_sub_f32_e32 v110, v111, v135
	v_cndmask_b32_e64 v85, 0, 32, vcc
	v_ldexp_f32 v85, v131, v85
	v_log_f32_e32 v116, v85
	v_max_f32_e32 v85, v115, v115
	v_min_f32_e32 v85, 0, v85
	v_mul_f32_e32 v111, 0x3f317217, v116
	v_fma_f32 v111, v116, s75, -v111
	v_fmac_f32_e32 v111, 0x3377d1cf, v116
	v_fmac_f32_e32 v111, 0x3f317217, v116
	v_cmp_lt_f32_e64 s[14:15], |v116|, s63
	s_nop 1
	v_cndmask_b32_e64 v111, v116, v111, s[14:15]
	v_cndmask_b32_e32 v116, 0, v226, vcc
	v_sub_f32_e32 v111, v111, v116
	v_pk_add_f32 v[84:85], v[84:85], v[110:111] neg_lo:[0,1] neg_hi:[0,1]
	s_nop 0
	v_pk_add_f32 v[110:111], v[84:85], v[122:123]
	s_nop 0
	v_pk_add_f32 v[116:117], v[110:111], v[118:119] neg_lo:[0,1] neg_hi:[0,1]
	s_nop 0
	v_mul_f32_e64 v84, |v116|, s69
	v_exp_f32_e32 v122, v84
	v_pk_mul_f32 v[84:85], v[92:93], v[124:125]
	v_rcp_f32_e32 v92, v130
	v_pk_mul_f32 v[84:85], v[106:107], v[84:85]
	v_add_f32_e32 v93, 1.0, v122
	v_cmp_gt_f32_e32 vcc, s74, v93
	s_nop 1
	v_cndmask_b32_e64 v106, 0, 32, vcc
	v_ldexp_f32 v93, v93, v106
	v_log_f32_e32 v107, v93
	v_max_f32_e32 v106, v118, v118
	v_mul_f32_e64 v118, |v117|, s69
	v_exp_f32_e32 v118, v118
	v_max_f32_e32 v106, v110, v106
	v_mul_f32_e32 v110, 0x3f317217, v107
	v_fma_f32 v110, v107, s75, -v110
	v_fmac_f32_e32 v110, 0x3377d1cf, v107
	v_fmac_f32_e32 v110, 0x3f317217, v107
	v_cmp_lt_f32_e64 s[14:15], |v107|, s63
	v_add_f32_e32 v118, 1.0, v118
	v_rcp_f32_e32 v93, v131
	v_cndmask_b32_e64 v107, v107, v110, s[14:15]
	v_cndmask_b32_e32 v110, 0, v226, vcc
	v_cmp_gt_f32_e32 vcc, s74, v118
	v_sub_f32_e32 v110, v107, v110
	s_nop 0
	v_cndmask_b32_e64 v122, 0, 32, vcc
	v_ldexp_f32 v118, v118, v122
	v_log_f32_e32 v118, v118
	v_max_f32_e32 v107, v111, v119
	v_mul_f32_e32 v111, 0x3f317217, v118
	v_fma_f32 v111, v118, s75, -v111
	v_fmac_f32_e32 v111, 0x3377d1cf, v118
	v_fmac_f32_e32 v111, 0x3f317217, v118
	v_cmp_lt_f32_e64 s[14:15], |v118|, s63
	s_nop 1
	v_cndmask_b32_e64 v111, v118, v111, s[14:15]
	v_cndmask_b32_e32 v118, 0, v226, vcc
	v_cmp_lt_f32_e64 vcc, |v103|, s49
	v_sub_f32_e32 v111, v111, v118
	s_nop 0
	v_cndmask_b32_e32 v103, 0, v121, vcc
	v_cmp_lt_f32_e64 vcc, |v102|, s49
	s_nop 1
	v_cndmask_b32_e32 v102, 0, v120, vcc
	v_cmp_lt_f32_e64 vcc, |v117|, s49
	s_nop 1
	v_cndmask_b32_e32 v111, 0, v111, vcc
	v_cmp_lt_f32_e64 vcc, |v116|, s49
	v_pk_add_f32 v[116:117], v[88:89], v[102:103]
	s_nop 0
	v_cndmask_b32_e32 v110, 0, v110, vcc
	v_cmp_lt_f32_e32 vcc, 0, v115
	v_pk_add_f32 v[118:119], v[106:107], v[110:111]
	s_nop 0
	v_cndmask_b32_e32 v89, 1.0, v129, vcc
	v_cmp_lt_f32_e32 vcc, 0, v114
	s_nop 1
	v_cndmask_b32_e32 v88, 1.0, v128, vcc
	v_pk_mul_f32 v[88:89], v[88:89], v[126:127]
	s_nop 0
	v_pk_mul_f32 v[88:89], v[92:93], v[88:89]
	v_lshl_add_u64 v[92:93], v[136:137], 2, s[94:95]
	global_store_dwordx4 v[92:93], v[116:119], off

.LBB0_1298:
	s_add_u32 s0, s22, s0
	s_addc_u32 s1, s23, s1
	v_mov_b32_e32 v135, v134
	v_lshl_add_u64 v[84:85], v[84:85], 1, s[0:1]
	v_cvt_pk_bf16_f32 v88, v88, v89
	v_cvt_pk_bf16_f32 v89, v90, v91
	v_or_b32_e32 v132, v132, v168
	v_pk_mul_f32 v[102:103], v[86:87], v[134:135]
	s_and_b64 vcc, exec, s[10:11]
	s_mov_b64 s[0:1], -1
	global_store_dwordx2 v[84:85], v[88:89], off offset:16
	s_cbranch_vccnz .LBB0_1300
	v_lshlrev_b32_e32 v84, 2, v194
	v_lshlrev_b32_e32 v92, 2, v168
	global_load_dwordx4 v[88:91], v84, s[86:87] offset:48
	s_nop 0
	global_load_dwordx4 v[84:87], v92, s[66:67]
	v_mul_f32_e64 v104, |v100|, s69
	global_load_dwordx4 v[92:95], v92, s[56:57]
	v_max_f32_e32 v105, v100, v100
	v_mul_f32_e64 v106, |v101|, s69
	v_exp_f32_e32 v113, v104
	v_min_f32_e32 v108, 0, v105
	v_exp_f32_e32 v105, v106
	v_max_f32_e32 v107, v101, v101
	v_mul_f32_e64 v112, |v103|, s69
	v_cmp_lt_f32_e32 vcc, 0, v101
	v_min_f32_e32 v109, 0, v107
	v_exp_f32_e32 v115, v112
	v_add_f32_e32 v112, 1.0, v113
	v_cndmask_b32_e32 v107, 1.0, v105, vcc
	v_cmp_lt_f32_e32 vcc, 0, v100
	v_add_f32_e32 v116, 1.0, v105
	v_cmp_gt_f32_e64 s[14:15], s74, v116
	v_cndmask_b32_e32 v106, 1.0, v113, vcc
	v_cmp_gt_f32_e32 vcc, s74, v112
	v_cndmask_b32_e64 v113, 0, 32, s[14:15]
	v_ldexp_f32 v113, v116, v113
	v_cndmask_b32_e64 v105, 0, 32, vcc
	v_ldexp_f32 v105, v112, v105
	v_log_f32_e32 v105, v105
	v_log_f32_e32 v113, v113
	v_mul_f32_e64 v110, |v102|, s69
	v_exp_f32_e32 v114, v110
	v_mul_f32_e32 v121, 0x3f317217, v105
	v_mul_f32_e32 v122, 0x3f317217, v113
	v_fma_f32 v121, v105, s75, -v121
	v_fma_f32 v122, v113, s75, -v122
	v_fmac_f32_e32 v121, 0x3377d1cf, v105
	v_rcp_f32_e32 v110, v112
	v_cndmask_b32_e32 v112, 0, v226, vcc
	v_fmac_f32_e32 v122, 0x3377d1cf, v113
	v_fmac_f32_e32 v121, 0x3f317217, v105
	v_cmp_lt_f32_e64 vcc, |v105|, s63
	v_max_f32_e32 v111, v102, v102
	v_add_f32_e32 v117, 1.0, v114
	v_fmac_f32_e32 v122, 0x3f317217, v113
	v_cndmask_b32_e32 v105, v105, v121, vcc
	v_cmp_lt_f32_e64 vcc, |v113|, s63
	v_min_f32_e32 v104, 0, v111
	v_rcp_f32_e32 v111, v116
	v_cmp_gt_f32_e64 s[16:17], s74, v117
	v_cndmask_b32_e64 v116, 0, v226, s[14:15]
	v_cndmask_b32_e32 v113, v113, v122, vcc
	v_cndmask_b32_e64 v119, 0, 32, s[16:17]
	v_sub_f32_e32 v112, v105, v112
	v_sub_f32_e32 v113, v113, v116
	v_ldexp_f32 v119, v117, v119
	v_pk_add_f32 v[108:109], v[108:109], v[112:113] neg_lo:[0,1] neg_hi:[0,1]
	v_log_f32_e32 v119, v119
	v_add_f32_e32 v118, 1.0, v115
	v_cndmask_b32_e64 v120, 0, v226, s[16:17]
	s_mov_b64 s[0:1], 0
	v_mul_f32_e32 v123, 0x3f317217, v119
	v_fma_f32 v123, v119, s75, -v123
	v_fmac_f32_e32 v123, 0x3377d1cf, v119
	v_fmac_f32_e32 v123, 0x3f317217, v119
	v_cmp_lt_f32_e64 vcc, |v119|, s63
	s_waitcnt vmcnt(0)
	v_pk_add_f32 v[108:109], v[108:109], v[88:89]
	s_nop 0
	v_pk_add_f32 v[88:89], v[108:109], v[84:85] neg_lo:[0,1] neg_hi:[0,1]
	v_max_f32_e32 v105, v84, v84
	v_mul_f32_e64 v84, |v88|, s69
	v_max_f32_e32 v112, v85, v85
	v_mul_f32_e64 v85, |v89|, s69
	v_exp_f32_e32 v113, v84
	v_exp_f32_e32 v116, v85
	v_max_f32_e32 v84, v108, v105
	v_cndmask_b32_e32 v119, v119, v123, vcc
	v_add_f32_e32 v105, 1.0, v113
	v_add_f32_e32 v108, 1.0, v116
	v_cmp_gt_f32_e32 vcc, s74, v105
	v_max_f32_e32 v85, v109, v112
	v_cmp_gt_f32_e64 s[14:15], s74, v108
	v_cndmask_b32_e64 v109, 0, 32, vcc
	v_ldexp_f32 v105, v105, v109
	v_cndmask_b32_e64 v112, 0, 32, s[14:15]
	v_ldexp_f32 v108, v108, v112
	v_log_f32_e32 v105, v105
	v_log_f32_e32 v108, v108
	v_cndmask_b32_e32 v109, 0, v226, vcc
	v_cndmask_b32_e64 v112, 0, v226, s[14:15]
	v_mul_f32_e32 v113, 0x3f317217, v105
	v_mul_f32_e32 v116, 0x3f317217, v108
	v_fma_f32 v113, v105, s75, -v113
	v_fma_f32 v116, v108, s75, -v116
	v_fmac_f32_e32 v113, 0x3377d1cf, v105
	v_fmac_f32_e32 v116, 0x3377d1cf, v108
	v_fmac_f32_e32 v113, 0x3f317217, v105
	v_cmp_lt_f32_e64 vcc, |v105|, s63
	v_fmac_f32_e32 v116, 0x3f317217, v108
	v_pk_mul_f32 v[92:93], v[106:107], v[92:93]
	v_cndmask_b32_e32 v105, v105, v113, vcc
	v_cmp_lt_f32_e64 vcc, |v108|, s63
	v_sub_f32_e32 v113, v105, v109
	v_pk_mul_f32 v[92:93], v[110:111], v[92:93]
	v_cndmask_b32_e32 v108, v108, v116, vcc
	v_cmp_gt_f32_e32 vcc, s74, v118
	v_sub_f32_e32 v112, v108, v112
	v_sub_f32_e32 v108, v119, v120
	v_cndmask_b32_e64 v105, 0, 32, vcc
	v_ldexp_f32 v105, v118, v105
	v_log_f32_e32 v109, v105
	v_max_f32_e32 v105, v103, v103
	v_min_f32_e32 v105, 0, v105
	v_rcp_f32_e32 v106, v117
	v_mul_f32_e32 v116, 0x3f317217, v109
	v_fma_f32 v116, v109, s75, -v116
	v_fmac_f32_e32 v116, 0x3377d1cf, v109
	v_fmac_f32_e32 v116, 0x3f317217, v109
	v_cmp_lt_f32_e64 s[14:15], |v109|, s63
	s_nop 1
	v_cndmask_b32_e64 v109, v109, v116, s[14:15]
	v_cndmask_b32_e32 v116, 0, v226, vcc
	v_sub_f32_e32 v109, v109, v116
	v_pk_add_f32 v[104:105], v[104:105], v[108:109] neg_lo:[0,1] neg_hi:[0,1]
	s_nop 0
	v_pk_add_f32 v[90:91], v[104:105], v[90:91]
	s_nop 0
	v_pk_add_f32 v[104:105], v[90:91], v[86:87] neg_lo:[0,1] neg_hi:[0,1]
	v_mul_f32_e64 v108, |v104|, s69
	v_exp_f32_e32 v108, v108
	v_mul_f32_e64 v109, |v105|, s69
	v_exp_f32_e32 v109, v109
	v_max_f32_e32 v86, v90, v86
	v_add_f32_e32 v107, 1.0, v108
	v_cmp_gt_f32_e32 vcc, s74, v107
	v_add_f32_e32 v109, 1.0, v109
	s_nop 0
	v_cndmask_b32_e64 v108, 0, 32, vcc
	v_ldexp_f32 v107, v107, v108
	v_log_f32_e32 v108, v107
	v_max_f32_e32 v87, v91, v87
	v_rcp_f32_e32 v107, v118
	v_mul_f32_e32 v90, 0x3f317217, v108
	v_fma_f32 v90, v108, s75, -v90
	v_fmac_f32_e32 v90, 0x3377d1cf, v108
	v_fmac_f32_e32 v90, 0x3f317217, v108
	v_cmp_lt_f32_e64 s[14:15], |v108|, s63
	s_nop 1
	v_cndmask_b32_e64 v90, v108, v90, s[14:15]
	v_cndmask_b32_e32 v108, 0, v226, vcc
	v_cmp_gt_f32_e32 vcc, s74, v109
	v_sub_f32_e32 v90, v90, v108
	s_nop 0
	v_cndmask_b32_e64 v110, 0, 32, vcc
	v_ldexp_f32 v109, v109, v110
	v_log_f32_e32 v109, v109
	v_cndmask_b32_e32 v108, 0, v226, vcc
	v_cmp_lt_f32_e64 vcc, |v89|, s49
	v_mul_f32_e32 v91, 0x3f317217, v109
	v_fma_f32 v91, v109, s75, -v91
	v_fmac_f32_e32 v91, 0x3377d1cf, v109
	v_fmac_f32_e32 v91, 0x3f317217, v109
	v_cmp_lt_f32_e64 s[14:15], |v109|, s63
	v_cndmask_b32_e32 v89, 0, v112, vcc
	v_cmp_lt_f32_e64 vcc, |v88|, s49
	v_cndmask_b32_e64 v91, v109, v91, s[14:15]
	v_sub_f32_e32 v91, v91, v108
	v_cndmask_b32_e32 v88, 0, v113, vcc
	v_cmp_lt_f32_e64 vcc, |v105|, s49
	v_pk_add_f32 v[84:85], v[84:85], v[88:89]
	s_nop 0
	v_cndmask_b32_e32 v91, 0, v91, vcc
	v_cmp_lt_f32_e64 vcc, |v104|, s49
	s_nop 1
	v_cndmask_b32_e32 v90, 0, v90, vcc
	v_cmp_lt_f32_e32 vcc, 0, v103
	v_pk_add_f32 v[86:87], v[86:87], v[90:91]
	v_lshl_add_u64 v[90:91], v[132:133], 2, s[94:95]
	v_cndmask_b32_e32 v89, 1.0, v115, vcc
	v_cmp_lt_f32_e32 vcc, 0, v102
	global_store_dwordx4 v[90:91], v[84:87], off
	s_nop 0
	v_cndmask_b32_e32 v88, 1.0, v114, vcc
	v_pk_mul_f32 v[88:89], v[88:89], v[94:95]
	v_lshl_add_u64 v[84:85], v[132:133], 1, s[84:85]
	v_pk_mul_f32 v[88:89], v[106:107], v[88:89]
	v_cvt_pk_bf16_f32 v86, v92, v93
	v_cvt_pk_bf16_f32 v87, v88, v89
	global_store_dwordx2 v[84:85], v[86:87], off

.LBB0_1321:
	s_and_b64 vcc, exec, s[0:1]
	s_cbranch_vccz .LBB0_1338
	s_and_b64 vcc, exec, s[10:11]
	s_mov_b64 s[0:1], -1
	s_cbranch_vccnz .LBB0_1324
	v_lshlrev_b32_e32 v68, 2, v194
	global_load_dwordx4 v[100:103], v68, s[86:87]
	global_load_dwordx4 v[96:99], v68, s[66:67]
	global_load_dwordx4 v[104:107], v68, s[56:57]
	v_mul_f32_e64 v69, |v92|, s69
	v_max_f32_e32 v72, v92, v92
	v_mul_f32_e64 v73, |v93|, s69
	v_exp_f32_e32 v86, v69
	v_min_f32_e32 v68, 0, v72
	v_exp_f32_e32 v72, v73
	v_mul_f32_e64 v83, |v95|, s69
	v_cmp_lt_f32_e32 vcc, 0, v93
	v_max_f32_e32 v76, v93, v93
	v_mul_f32_e64 v77, |v94|, s69
	v_max_f32_e32 v82, v94, v94
	v_exp_f32_e32 v91, v83
	v_add_f32_e32 v73, 1.0, v86
	v_cndmask_b32_e32 v83, 1.0, v72, vcc
	v_cmp_lt_f32_e32 vcc, 0, v92
	v_min_f32_e32 v69, 0, v76
	v_exp_f32_e32 v90, v77
	v_min_f32_e32 v76, 0, v82
	v_add_f32_e32 v77, 1.0, v72
	v_cndmask_b32_e32 v82, 1.0, v86, vcc
	v_cmp_gt_f32_e32 vcc, s74, v73
	v_cmp_gt_f32_e64 s[14:15], s74, v77
	v_rcp_f32_e32 v87, v77
	v_cndmask_b32_e64 v72, 0, 32, vcc
	v_cndmask_b32_e64 v110, 0, 32, s[14:15]
	v_ldexp_f32 v72, v73, v72
	v_ldexp_f32 v77, v77, v110
	v_log_f32_e32 v72, v72
	v_log_f32_e32 v77, v77
	v_rcp_f32_e32 v86, v73
	v_cndmask_b32_e32 v73, 0, v226, vcc
	v_mul_f32_e32 v118, 0x3f317217, v72
	v_mul_f32_e32 v119, 0x3f317217, v77
	v_fma_f32 v118, v72, s75, -v118
	v_fma_f32 v119, v77, s75, -v119
	v_fmac_f32_e32 v118, 0x3377d1cf, v72
	v_fmac_f32_e32 v119, 0x3377d1cf, v77
	v_fmac_f32_e32 v118, 0x3f317217, v72
	v_cmp_lt_f32_e64 vcc, |v72|, s63
	v_add_f32_e32 v108, 1.0, v90
	v_fmac_f32_e32 v119, 0x3f317217, v77
	v_cndmask_b32_e32 v72, v72, v118, vcc
	v_cmp_lt_f32_e64 vcc, |v77|, s63
	v_cmp_gt_f32_e64 s[16:17], s74, v108
	v_cndmask_b32_e64 v110, 0, v226, s[14:15]
	v_cndmask_b32_e32 v77, v77, v119, vcc
	v_cndmask_b32_e64 v111, 0, 32, s[16:17]
	v_sub_f32_e32 v72, v72, v73
	v_sub_f32_e32 v73, v77, v110
	v_ldexp_f32 v111, v108, v111
	v_pk_add_f32 v[68:69], v[68:69], v[72:73] neg_lo:[0,1] neg_hi:[0,1]
	v_log_f32_e32 v111, v111
	v_add_f32_e32 v109, 1.0, v91
	v_cndmask_b32_e64 v115, 0, v226, s[16:17]
	s_mov_b64 s[0:1], 0
	v_mul_f32_e32 v120, 0x3f317217, v111
	v_fma_f32 v120, v111, s75, -v120
	v_fmac_f32_e32 v120, 0x3377d1cf, v111
	v_fmac_f32_e32 v120, 0x3f317217, v111
	v_cmp_lt_f32_e64 vcc, |v111|, s63
	s_waitcnt vmcnt(0)
	v_pk_add_f32 v[68:69], v[68:69], v[100:101]
	s_nop 0
	v_pk_add_f32 v[72:73], v[68:69], v[96:97] neg_lo:[0,1] neg_hi:[0,1]
	v_max_f32_e32 v77, v96, v96
	v_mul_f32_e64 v96, |v72|, s69
	v_max_f32_e32 v100, v97, v97
	v_mul_f32_e64 v97, |v73|, s69
	v_exp_f32_e32 v96, v96
	v_exp_f32_e32 v97, v97
	v_max_f32_e32 v68, v68, v77
	v_cndmask_b32_e32 v111, v111, v120, vcc
	v_add_f32_e32 v77, 1.0, v96
	v_add_f32_e32 v96, 1.0, v97
	v_cmp_gt_f32_e32 vcc, s74, v77
	v_cmp_gt_f32_e64 s[14:15], s74, v96
	v_max_f32_e32 v69, v69, v100
	v_cndmask_b32_e64 v97, 0, 32, vcc
	v_cndmask_b32_e64 v100, 0, 32, s[14:15]
	v_ldexp_f32 v77, v77, v97
	v_ldexp_f32 v96, v96, v100
	v_log_f32_e32 v77, v77
	v_log_f32_e32 v96, v96
	v_cndmask_b32_e32 v97, 0, v226, vcc
	v_cndmask_b32_e64 v100, 0, v226, s[14:15]
	v_mul_f32_e32 v101, 0x3f317217, v77
	v_mul_f32_e32 v110, 0x3f317217, v96
	v_fma_f32 v101, v77, s75, -v101
	v_fma_f32 v110, v96, s75, -v110
	v_fmac_f32_e32 v101, 0x3377d1cf, v77
	v_fmac_f32_e32 v110, 0x3377d1cf, v96
	v_fmac_f32_e32 v101, 0x3f317217, v77
	v_cmp_lt_f32_e64 vcc, |v77|, s63
	v_fmac_f32_e32 v110, 0x3f317217, v96
	s_nop 0
	v_cndmask_b32_e32 v77, v77, v101, vcc
	v_cmp_lt_f32_e64 vcc, |v96|, s63
	s_nop 1
	v_cndmask_b32_e32 v96, v96, v110, vcc
	v_cmp_gt_f32_e32 vcc, s74, v109
	v_sub_f32_e32 v110, v77, v97
	v_sub_f32_e32 v118, v96, v100
	v_cndmask_b32_e64 v77, 0, 32, vcc
	v_ldexp_f32 v77, v109, v77
	v_log_f32_e32 v97, v77
	v_max_f32_e32 v77, v95, v95
	v_sub_f32_e32 v96, v111, v115
	v_min_f32_e32 v77, 0, v77
	v_mul_f32_e32 v100, 0x3f317217, v97
	v_fma_f32 v100, v97, s75, -v100
	v_fmac_f32_e32 v100, 0x3377d1cf, v97
	v_fmac_f32_e32 v100, 0x3f317217, v97
	v_cmp_lt_f32_e64 s[14:15], |v97|, s63
	s_nop 1
	v_cndmask_b32_e64 v97, v97, v100, s[14:15]
	v_cndmask_b32_e32 v100, 0, v226, vcc
	v_sub_f32_e32 v97, v97, v100
	v_pk_add_f32 v[76:77], v[76:77], v[96:97] neg_lo:[0,1] neg_hi:[0,1]
	s_nop 0
	v_pk_add_f32 v[96:97], v[76:77], v[102:103]
	s_nop 0
	v_pk_add_f32 v[100:101], v[96:97], v[98:99] neg_lo:[0,1] neg_hi:[0,1]
	s_nop 0
	v_mul_f32_e64 v76, |v100|, s69
	v_exp_f32_e32 v102, v76
	v_pk_mul_f32 v[76:77], v[82:83], v[104:105]
	v_rcp_f32_e32 v82, v108
	v_pk_mul_f32 v[76:77], v[86:87], v[76:77]
	v_add_f32_e32 v83, 1.0, v102
	v_cmp_gt_f32_e32 vcc, s74, v83
	s_nop 1
	v_cndmask_b32_e64 v86, 0, 32, vcc
	v_ldexp_f32 v83, v83, v86
	v_log_f32_e32 v87, v83
	v_max_f32_e32 v86, v98, v98
	v_mul_f32_e64 v98, |v101|, s69
	v_exp_f32_e32 v98, v98
	v_max_f32_e32 v86, v96, v86
	v_mul_f32_e32 v96, 0x3f317217, v87
	v_fma_f32 v96, v87, s75, -v96
	v_fmac_f32_e32 v96, 0x3377d1cf, v87
	v_fmac_f32_e32 v96, 0x3f317217, v87
	v_cmp_lt_f32_e64 s[14:15], |v87|, s63
	v_add_f32_e32 v98, 1.0, v98
	v_rcp_f32_e32 v83, v109
	v_cndmask_b32_e64 v87, v87, v96, s[14:15]
	v_cndmask_b32_e32 v96, 0, v226, vcc
	v_cmp_gt_f32_e32 vcc, s74, v98
	v_sub_f32_e32 v96, v87, v96
	s_nop 0
	v_cndmask_b32_e64 v102, 0, 32, vcc
	v_ldexp_f32 v98, v98, v102
	v_log_f32_e32 v98, v98
	v_max_f32_e32 v87, v97, v99
	v_mul_f32_e32 v97, 0x3f317217, v98
	v_fma_f32 v97, v98, s75, -v97
	v_fmac_f32_e32 v97, 0x3377d1cf, v98
	v_fmac_f32_e32 v97, 0x3f317217, v98
	v_cmp_lt_f32_e64 s[14:15], |v98|, s63
	s_nop 1
	v_cndmask_b32_e64 v97, v98, v97, s[14:15]
	v_cndmask_b32_e32 v98, 0, v226, vcc
	v_cmp_lt_f32_e64 vcc, |v73|, s49
	v_sub_f32_e32 v97, v97, v98
	s_nop 0
	v_cndmask_b32_e32 v73, 0, v118, vcc
	v_cmp_lt_f32_e64 vcc, |v72|, s49
	s_nop 1
	v_cndmask_b32_e32 v72, 0, v110, vcc
	v_cmp_lt_f32_e64 vcc, |v101|, s49
	s_nop 1
	v_cndmask_b32_e32 v97, 0, v97, vcc
	v_cmp_lt_f32_e64 vcc, |v100|, s49
	s_nop 1
	v_cndmask_b32_e32 v96, 0, v96, vcc
	v_cmp_lt_f32_e32 vcc, 0, v95
	v_pk_add_f32 v[98:99], v[86:87], v[96:97]
	v_pk_add_f32 v[96:97], v[68:69], v[72:73]
	v_cndmask_b32_e32 v69, 1.0, v91, vcc
	v_cmp_lt_f32_e32 vcc, 0, v94
	v_lshl_add_u64 v[72:73], v[116:117], 2, s[94:95]
	global_store_dwordx4 v[72:73], v[96:99], off
	v_cndmask_b32_e32 v68, 1.0, v90, vcc
	v_pk_mul_f32 v[68:69], v[68:69], v[106:107]
	s_nop 0
	v_pk_mul_f32 v[68:69], v[82:83], v[68:69]

.LBB0_1334:
	s_add_u32 s0, s22, s0
	s_addc_u32 s1, s23, s1
	v_mov_b32_e32 v115, v114
	v_lshl_add_u64 v[68:69], v[68:69], 1, s[0:1]
	v_cvt_pk_bf16_f32 v72, v72, v73
	v_cvt_pk_bf16_f32 v73, v74, v75
	v_or_b32_e32 v112, v112, v168
	v_pk_mul_f32 v[82:83], v[70:71], v[114:115]
	s_and_b64 vcc, exec, s[10:11]
	s_mov_b64 s[0:1], -1
	global_store_dwordx2 v[68:69], v[72:73], off offset:16
	s_cbranch_vccnz .LBB0_1336
	v_lshlrev_b32_e32 v68, 2, v194
	v_lshlrev_b32_e32 v76, 2, v168
	global_load_dwordx4 v[72:75], v68, s[86:87] offset:48
	s_nop 0
	global_load_dwordx4 v[68:71], v76, s[66:67]
	v_mul_f32_e64 v84, |v80|, s69
	global_load_dwordx4 v[76:79], v76, s[56:57]
	v_max_f32_e32 v85, v80, v80
	v_mul_f32_e64 v86, |v81|, s69
	v_exp_f32_e32 v93, v84
	v_min_f32_e32 v88, 0, v85
	v_exp_f32_e32 v85, v86
	v_max_f32_e32 v87, v81, v81
	v_mul_f32_e64 v92, |v83|, s69
	v_cmp_lt_f32_e32 vcc, 0, v81
	v_min_f32_e32 v89, 0, v87
	v_exp_f32_e32 v95, v92
	v_add_f32_e32 v92, 1.0, v93
	v_cndmask_b32_e32 v87, 1.0, v85, vcc
	v_cmp_lt_f32_e32 vcc, 0, v80
	v_add_f32_e32 v96, 1.0, v85
	v_cmp_gt_f32_e64 s[14:15], s74, v96
	v_cndmask_b32_e32 v86, 1.0, v93, vcc
	v_cmp_gt_f32_e32 vcc, s74, v92
	v_cndmask_b32_e64 v93, 0, 32, s[14:15]
	v_ldexp_f32 v93, v96, v93
	v_cndmask_b32_e64 v85, 0, 32, vcc
	v_ldexp_f32 v85, v92, v85
	v_log_f32_e32 v85, v85
	v_log_f32_e32 v93, v93
	v_mul_f32_e64 v90, |v82|, s69
	v_exp_f32_e32 v94, v90
	v_mul_f32_e32 v101, 0x3f317217, v85
	v_mul_f32_e32 v102, 0x3f317217, v93
	v_fma_f32 v101, v85, s75, -v101
	v_fma_f32 v102, v93, s75, -v102
	v_fmac_f32_e32 v101, 0x3377d1cf, v85
	v_rcp_f32_e32 v90, v92
	v_cndmask_b32_e32 v92, 0, v226, vcc
	v_fmac_f32_e32 v102, 0x3377d1cf, v93
	v_fmac_f32_e32 v101, 0x3f317217, v85
	v_cmp_lt_f32_e64 vcc, |v85|, s63
	v_max_f32_e32 v91, v82, v82
	v_add_f32_e32 v97, 1.0, v94
	v_fmac_f32_e32 v102, 0x3f317217, v93
	v_cndmask_b32_e32 v85, v85, v101, vcc
	v_cmp_lt_f32_e64 vcc, |v93|, s63
	v_min_f32_e32 v84, 0, v91
	v_rcp_f32_e32 v91, v96
	v_cmp_gt_f32_e64 s[16:17], s74, v97
	v_cndmask_b32_e64 v96, 0, v226, s[14:15]
	v_cndmask_b32_e32 v93, v93, v102, vcc
	v_cndmask_b32_e64 v99, 0, 32, s[16:17]
	v_sub_f32_e32 v92, v85, v92
	v_sub_f32_e32 v93, v93, v96
	v_ldexp_f32 v99, v97, v99
	v_pk_add_f32 v[88:89], v[88:89], v[92:93] neg_lo:[0,1] neg_hi:[0,1]
	v_log_f32_e32 v99, v99
	v_add_f32_e32 v98, 1.0, v95
	v_cndmask_b32_e64 v100, 0, v226, s[16:17]
	s_mov_b64 s[0:1], 0
	v_mul_f32_e32 v103, 0x3f317217, v99
	v_fma_f32 v103, v99, s75, -v103
	v_fmac_f32_e32 v103, 0x3377d1cf, v99
	v_fmac_f32_e32 v103, 0x3f317217, v99
	v_cmp_lt_f32_e64 vcc, |v99|, s63
	s_waitcnt vmcnt(0)
	v_pk_add_f32 v[88:89], v[88:89], v[72:73]
	s_nop 0
	v_pk_add_f32 v[72:73], v[88:89], v[68:69] neg_lo:[0,1] neg_hi:[0,1]
	v_max_f32_e32 v85, v68, v68
	v_mul_f32_e64 v68, |v72|, s69
	v_max_f32_e32 v92, v69, v69
	v_mul_f32_e64 v69, |v73|, s69
	v_exp_f32_e32 v93, v68
	v_exp_f32_e32 v96, v69
	v_max_f32_e32 v68, v88, v85
	v_cndmask_b32_e32 v99, v99, v103, vcc
	v_add_f32_e32 v85, 1.0, v93
	v_add_f32_e32 v88, 1.0, v96
	v_cmp_gt_f32_e32 vcc, s74, v85
	v_max_f32_e32 v69, v89, v92
	v_cmp_gt_f32_e64 s[14:15], s74, v88
	v_cndmask_b32_e64 v89, 0, 32, vcc
	v_ldexp_f32 v85, v85, v89
	v_cndmask_b32_e64 v92, 0, 32, s[14:15]
	v_ldexp_f32 v88, v88, v92
	v_log_f32_e32 v85, v85
	v_log_f32_e32 v88, v88
	v_cndmask_b32_e32 v89, 0, v226, vcc
	v_cndmask_b32_e64 v92, 0, v226, s[14:15]
	v_mul_f32_e32 v93, 0x3f317217, v85
	v_mul_f32_e32 v96, 0x3f317217, v88
	v_fma_f32 v93, v85, s75, -v93
	v_fma_f32 v96, v88, s75, -v96
	v_fmac_f32_e32 v93, 0x3377d1cf, v85
	v_fmac_f32_e32 v96, 0x3377d1cf, v88
	v_fmac_f32_e32 v93, 0x3f317217, v85
	v_cmp_lt_f32_e64 vcc, |v85|, s63
	v_fmac_f32_e32 v96, 0x3f317217, v88
	v_pk_mul_f32 v[76:77], v[86:87], v[76:77]
	v_cndmask_b32_e32 v85, v85, v93, vcc
	v_cmp_lt_f32_e64 vcc, |v88|, s63
	v_sub_f32_e32 v93, v85, v89
	v_pk_mul_f32 v[76:77], v[90:91], v[76:77]
	v_cndmask_b32_e32 v88, v88, v96, vcc
	v_cmp_gt_f32_e32 vcc, s74, v98
	v_sub_f32_e32 v92, v88, v92
	v_sub_f32_e32 v88, v99, v100
	v_cndmask_b32_e64 v85, 0, 32, vcc
	v_ldexp_f32 v85, v98, v85
	v_log_f32_e32 v89, v85
	v_max_f32_e32 v85, v83, v83
	v_min_f32_e32 v85, 0, v85
	v_rcp_f32_e32 v86, v97
	v_mul_f32_e32 v96, 0x3f317217, v89
	v_fma_f32 v96, v89, s75, -v96
	v_fmac_f32_e32 v96, 0x3377d1cf, v89
	v_fmac_f32_e32 v96, 0x3f317217, v89
	v_cmp_lt_f32_e64 s[14:15], |v89|, s63
	s_nop 1
	v_cndmask_b32_e64 v89, v89, v96, s[14:15]
	v_cndmask_b32_e32 v96, 0, v226, vcc
	v_sub_f32_e32 v89, v89, v96
	v_pk_add_f32 v[84:85], v[84:85], v[88:89] neg_lo:[0,1] neg_hi:[0,1]
	s_nop 0
	v_pk_add_f32 v[74:75], v[84:85], v[74:75]
	s_nop 0
	v_pk_add_f32 v[84:85], v[74:75], v[70:71] neg_lo:[0,1] neg_hi:[0,1]
	v_mul_f32_e64 v88, |v84|, s69
	v_exp_f32_e32 v88, v88
	v_mul_f32_e64 v89, |v85|, s69
	v_exp_f32_e32 v89, v89
	v_max_f32_e32 v70, v74, v70
	v_add_f32_e32 v87, 1.0, v88
	v_cmp_gt_f32_e32 vcc, s74, v87
	v_add_f32_e32 v89, 1.0, v89
	s_nop 0
	v_cndmask_b32_e64 v88, 0, 32, vcc
	v_ldexp_f32 v87, v87, v88
	v_log_f32_e32 v88, v87
	v_max_f32_e32 v71, v75, v71
	v_rcp_f32_e32 v87, v98
	v_mul_f32_e32 v74, 0x3f317217, v88
	v_fma_f32 v74, v88, s75, -v74
	v_fmac_f32_e32 v74, 0x3377d1cf, v88
	v_fmac_f32_e32 v74, 0x3f317217, v88
	v_cmp_lt_f32_e64 s[14:15], |v88|, s63
	s_nop 1
	v_cndmask_b32_e64 v74, v88, v74, s[14:15]
	v_cndmask_b32_e32 v88, 0, v226, vcc
	v_cmp_gt_f32_e32 vcc, s74, v89
	v_sub_f32_e32 v74, v74, v88
	s_nop 0
	v_cndmask_b32_e64 v90, 0, 32, vcc
	v_ldexp_f32 v89, v89, v90
	v_log_f32_e32 v89, v89
	v_cndmask_b32_e32 v88, 0, v226, vcc
	v_cmp_lt_f32_e64 vcc, |v73|, s49
	v_mul_f32_e32 v75, 0x3f317217, v89
	v_fma_f32 v75, v89, s75, -v75
	v_fmac_f32_e32 v75, 0x3377d1cf, v89
	v_fmac_f32_e32 v75, 0x3f317217, v89
	v_cmp_lt_f32_e64 s[14:15], |v89|, s63
	v_cndmask_b32_e32 v73, 0, v92, vcc
	v_cmp_lt_f32_e64 vcc, |v72|, s49
	v_cndmask_b32_e64 v75, v89, v75, s[14:15]
	v_sub_f32_e32 v75, v75, v88
	v_cndmask_b32_e32 v72, 0, v93, vcc
	v_cmp_lt_f32_e64 vcc, |v85|, s49
	v_pk_add_f32 v[68:69], v[68:69], v[72:73]
	s_nop 0
	v_cndmask_b32_e32 v75, 0, v75, vcc
	v_cmp_lt_f32_e64 vcc, |v84|, s49
	s_nop 1
	v_cndmask_b32_e32 v74, 0, v74, vcc
	v_cmp_lt_f32_e32 vcc, 0, v83
	v_pk_add_f32 v[70:71], v[70:71], v[74:75]
	v_lshl_add_u64 v[74:75], v[112:113], 2, s[94:95]
	v_cndmask_b32_e32 v73, 1.0, v95, vcc
	v_cmp_lt_f32_e32 vcc, 0, v82
	global_store_dwordx4 v[74:75], v[68:71], off
	s_nop 0
	v_cndmask_b32_e32 v72, 1.0, v94, vcc
	v_pk_mul_f32 v[72:73], v[72:73], v[78:79]
	v_lshl_add_u64 v[68:69], v[112:113], 1, s[84:85]
	v_pk_mul_f32 v[72:73], v[86:87], v[72:73]
	v_cvt_pk_bf16_f32 v70, v76, v77
	v_cvt_pk_bf16_f32 v71, v72, v73
	global_store_dwordx2 v[68:69], v[70:71], off

.LBB0_1373:
	s_and_b64 vcc, exec, s[0:1]
	s_cbranch_vccz .LBB0_1390
	s_and_b64 vcc, exec, s[10:11]
	s_mov_b64 s[0:1], -1
	s_cbranch_vccnz .LBB0_1376
	v_lshlrev_b32_e32 v52, 2, v194
	global_load_dwordx4 v[96:99], v52, s[86:87]
	global_load_dwordx4 v[92:95], v52, s[66:67]
	global_load_dwordx4 v[100:103], v52, s[56:57]
	v_mul_f32_e64 v53, |v88|, s69
	v_max_f32_e32 v56, v88, v88
	v_mul_f32_e64 v57, |v89|, s69
	v_exp_f32_e32 v82, v53
	v_min_f32_e32 v52, 0, v56
	v_exp_f32_e32 v56, v57
	v_mul_f32_e64 v67, |v91|, s69
	v_cmp_lt_f32_e32 vcc, 0, v89
	v_max_f32_e32 v60, v89, v89
	v_mul_f32_e64 v61, |v90|, s69
	v_max_f32_e32 v66, v90, v90
	v_exp_f32_e32 v87, v67
	v_add_f32_e32 v57, 1.0, v82
	v_cndmask_b32_e32 v67, 1.0, v56, vcc
	v_cmp_lt_f32_e32 vcc, 0, v88
	v_min_f32_e32 v53, 0, v60
	v_exp_f32_e32 v86, v61
	v_min_f32_e32 v60, 0, v66
	v_add_f32_e32 v61, 1.0, v56
	v_cndmask_b32_e32 v66, 1.0, v82, vcc
	v_cmp_gt_f32_e32 vcc, s74, v57
	v_cmp_gt_f32_e64 s[14:15], s74, v61
	v_rcp_f32_e32 v83, v61
	v_cndmask_b32_e64 v56, 0, 32, vcc
	v_cndmask_b32_e64 v106, 0, 32, s[14:15]
	v_ldexp_f32 v56, v57, v56
	v_ldexp_f32 v61, v61, v106
	v_log_f32_e32 v56, v56
	v_log_f32_e32 v61, v61
	v_rcp_f32_e32 v82, v57
	v_cndmask_b32_e32 v57, 0, v226, vcc
	v_mul_f32_e32 v114, 0x3f317217, v56
	v_mul_f32_e32 v115, 0x3f317217, v61
	v_fma_f32 v114, v56, s75, -v114
	v_fma_f32 v115, v61, s75, -v115
	v_fmac_f32_e32 v114, 0x3377d1cf, v56
	v_fmac_f32_e32 v115, 0x3377d1cf, v61
	v_fmac_f32_e32 v114, 0x3f317217, v56
	v_cmp_lt_f32_e64 vcc, |v56|, s63
	v_add_f32_e32 v104, 1.0, v86
	v_fmac_f32_e32 v115, 0x3f317217, v61
	v_cndmask_b32_e32 v56, v56, v114, vcc
	v_cmp_lt_f32_e64 vcc, |v61|, s63
	v_cmp_gt_f32_e64 s[16:17], s74, v104
	v_cndmask_b32_e64 v106, 0, v226, s[14:15]
	v_cndmask_b32_e32 v61, v61, v115, vcc
	v_cndmask_b32_e64 v107, 0, 32, s[16:17]
	v_sub_f32_e32 v56, v56, v57
	v_sub_f32_e32 v57, v61, v106
	v_ldexp_f32 v107, v104, v107
	v_pk_add_f32 v[52:53], v[52:53], v[56:57] neg_lo:[0,1] neg_hi:[0,1]
	v_log_f32_e32 v107, v107
	v_add_f32_e32 v105, 1.0, v87
	v_cndmask_b32_e64 v111, 0, v226, s[16:17]
	s_mov_b64 s[0:1], 0
	v_mul_f32_e32 v116, 0x3f317217, v107
	v_fma_f32 v116, v107, s75, -v116
	v_fmac_f32_e32 v116, 0x3377d1cf, v107
	v_fmac_f32_e32 v116, 0x3f317217, v107
	v_cmp_lt_f32_e64 vcc, |v107|, s63
	s_waitcnt vmcnt(0)
	v_pk_add_f32 v[52:53], v[52:53], v[96:97]
	s_nop 0
	v_pk_add_f32 v[56:57], v[52:53], v[92:93] neg_lo:[0,1] neg_hi:[0,1]
	v_max_f32_e32 v61, v92, v92
	v_mul_f32_e64 v92, |v56|, s69
	v_max_f32_e32 v96, v93, v93
	v_mul_f32_e64 v93, |v57|, s69
	v_exp_f32_e32 v92, v92
	v_exp_f32_e32 v93, v93
	v_max_f32_e32 v52, v52, v61
	v_cndmask_b32_e32 v107, v107, v116, vcc
	v_add_f32_e32 v61, 1.0, v92
	v_add_f32_e32 v92, 1.0, v93
	v_cmp_gt_f32_e32 vcc, s74, v61
	v_cmp_gt_f32_e64 s[14:15], s74, v92
	v_max_f32_e32 v53, v53, v96
	v_cndmask_b32_e64 v93, 0, 32, vcc
	v_cndmask_b32_e64 v96, 0, 32, s[14:15]
	v_ldexp_f32 v61, v61, v93
	v_ldexp_f32 v92, v92, v96
	v_log_f32_e32 v61, v61
	v_log_f32_e32 v92, v92
	v_cndmask_b32_e32 v93, 0, v226, vcc
	v_cndmask_b32_e64 v96, 0, v226, s[14:15]
	v_mul_f32_e32 v97, 0x3f317217, v61
	v_mul_f32_e32 v106, 0x3f317217, v92
	v_fma_f32 v97, v61, s75, -v97
	v_fma_f32 v106, v92, s75, -v106
	v_fmac_f32_e32 v97, 0x3377d1cf, v61
	v_fmac_f32_e32 v106, 0x3377d1cf, v92
	v_fmac_f32_e32 v97, 0x3f317217, v61
	v_cmp_lt_f32_e64 vcc, |v61|, s63
	v_fmac_f32_e32 v106, 0x3f317217, v92
	s_nop 0
	v_cndmask_b32_e32 v61, v61, v97, vcc
	v_cmp_lt_f32_e64 vcc, |v92|, s63
	s_nop 1
	v_cndmask_b32_e32 v92, v92, v106, vcc
	v_cmp_gt_f32_e32 vcc, s74, v105
	v_sub_f32_e32 v106, v61, v93
	v_sub_f32_e32 v114, v92, v96
	v_cndmask_b32_e64 v61, 0, 32, vcc
	v_ldexp_f32 v61, v105, v61
	v_log_f32_e32 v93, v61
	v_max_f32_e32 v61, v91, v91
	v_sub_f32_e32 v92, v107, v111
	v_min_f32_e32 v61, 0, v61
	v_mul_f32_e32 v96, 0x3f317217, v93
	v_fma_f32 v96, v93, s75, -v96
	v_fmac_f32_e32 v96, 0x3377d1cf, v93
	v_fmac_f32_e32 v96, 0x3f317217, v93
	v_cmp_lt_f32_e64 s[14:15], |v93|, s63
	s_nop 1
	v_cndmask_b32_e64 v93, v93, v96, s[14:15]
	v_cndmask_b32_e32 v96, 0, v226, vcc
	v_sub_f32_e32 v93, v93, v96
	v_pk_add_f32 v[60:61], v[60:61], v[92:93] neg_lo:[0,1] neg_hi:[0,1]
	s_nop 0
	v_pk_add_f32 v[92:93], v[60:61], v[98:99]
	s_nop 0
	v_pk_add_f32 v[96:97], v[92:93], v[94:95] neg_lo:[0,1] neg_hi:[0,1]
	s_nop 0
	v_mul_f32_e64 v60, |v96|, s69
	v_exp_f32_e32 v98, v60
	v_pk_mul_f32 v[60:61], v[66:67], v[100:101]
	v_rcp_f32_e32 v66, v104
	v_pk_mul_f32 v[60:61], v[82:83], v[60:61]
	v_add_f32_e32 v67, 1.0, v98
	v_cmp_gt_f32_e32 vcc, s74, v67
	s_nop 1
	v_cndmask_b32_e64 v82, 0, 32, vcc
	v_ldexp_f32 v67, v67, v82
	v_log_f32_e32 v83, v67
	v_max_f32_e32 v82, v94, v94
	v_mul_f32_e64 v94, |v97|, s69
	v_exp_f32_e32 v94, v94
	v_max_f32_e32 v82, v92, v82
	v_mul_f32_e32 v92, 0x3f317217, v83
	v_fma_f32 v92, v83, s75, -v92
	v_fmac_f32_e32 v92, 0x3377d1cf, v83
	v_fmac_f32_e32 v92, 0x3f317217, v83
	v_cmp_lt_f32_e64 s[14:15], |v83|, s63
	v_add_f32_e32 v94, 1.0, v94
	v_rcp_f32_e32 v67, v105
	v_cndmask_b32_e64 v83, v83, v92, s[14:15]
	v_cndmask_b32_e32 v92, 0, v226, vcc
	v_cmp_gt_f32_e32 vcc, s74, v94
	v_sub_f32_e32 v92, v83, v92
	s_nop 0
	v_cndmask_b32_e64 v98, 0, 32, vcc
	v_ldexp_f32 v94, v94, v98
	v_log_f32_e32 v94, v94
	v_max_f32_e32 v83, v93, v95
	v_mul_f32_e32 v93, 0x3f317217, v94
	v_fma_f32 v93, v94, s75, -v93
	v_fmac_f32_e32 v93, 0x3377d1cf, v94
	v_fmac_f32_e32 v93, 0x3f317217, v94
	v_cmp_lt_f32_e64 s[14:15], |v94|, s63
	s_nop 1
	v_cndmask_b32_e64 v93, v94, v93, s[14:15]
	v_cndmask_b32_e32 v94, 0, v226, vcc
	v_cmp_lt_f32_e64 vcc, |v57|, s49
	v_sub_f32_e32 v93, v93, v94
	s_nop 0
	v_cndmask_b32_e32 v57, 0, v114, vcc
	v_cmp_lt_f32_e64 vcc, |v56|, s49
	s_nop 1
	v_cndmask_b32_e32 v56, 0, v106, vcc
	v_cmp_lt_f32_e64 vcc, |v97|, s49
	s_nop 1
	v_cndmask_b32_e32 v93, 0, v93, vcc
	v_cmp_lt_f32_e64 vcc, |v96|, s49
	s_nop 1
	v_cndmask_b32_e32 v92, 0, v92, vcc
	v_cmp_lt_f32_e32 vcc, 0, v91
	v_pk_add_f32 v[94:95], v[82:83], v[92:93]
	v_pk_add_f32 v[92:93], v[52:53], v[56:57]
	v_cndmask_b32_e32 v53, 1.0, v87, vcc
	v_cmp_lt_f32_e32 vcc, 0, v90
	v_lshl_add_u64 v[56:57], v[112:113], 2, s[94:95]
	global_store_dwordx4 v[56:57], v[92:95], off
	v_cndmask_b32_e32 v52, 1.0, v86, vcc
	v_pk_mul_f32 v[52:53], v[52:53], v[102:103]
	s_nop 0
	v_pk_mul_f32 v[52:53], v[66:67], v[52:53]

.LBB0_1386:
	s_add_u32 s0, s22, s0
	s_addc_u32 s1, s23, s1
	v_mov_b32_e32 v111, v110
	v_lshl_add_u64 v[52:53], v[52:53], 1, s[0:1]
	v_cvt_pk_bf16_f32 v56, v56, v57
	v_cvt_pk_bf16_f32 v57, v58, v59
	v_or_b32_e32 v108, v108, v168
	v_pk_mul_f32 v[66:67], v[54:55], v[110:111]
	s_and_b64 vcc, exec, s[10:11]
	s_mov_b64 s[0:1], -1
	global_store_dwordx2 v[52:53], v[56:57], off offset:16
	s_cbranch_vccnz .LBB0_1388
	v_lshlrev_b32_e32 v52, 2, v194
	v_lshlrev_b32_e32 v60, 2, v168
	global_load_dwordx4 v[56:59], v52, s[86:87] offset:48
	s_nop 0
	global_load_dwordx4 v[52:55], v60, s[66:67]
	v_mul_f32_e64 v80, |v64|, s69
	global_load_dwordx4 v[60:63], v60, s[56:57]
	v_max_f32_e32 v81, v64, v64
	v_mul_f32_e64 v82, |v65|, s69
	v_exp_f32_e32 v89, v80
	v_min_f32_e32 v84, 0, v81
	v_exp_f32_e32 v81, v82
	v_max_f32_e32 v83, v65, v65
	v_mul_f32_e64 v88, |v67|, s69
	v_cmp_lt_f32_e32 vcc, 0, v65
	v_min_f32_e32 v85, 0, v83
	v_exp_f32_e32 v91, v88
	v_add_f32_e32 v88, 1.0, v89
	v_cndmask_b32_e32 v83, 1.0, v81, vcc
	v_cmp_lt_f32_e32 vcc, 0, v64
	v_add_f32_e32 v92, 1.0, v81
	v_cmp_gt_f32_e64 s[14:15], s74, v92
	v_cndmask_b32_e32 v82, 1.0, v89, vcc
	v_cmp_gt_f32_e32 vcc, s74, v88
	v_cndmask_b32_e64 v89, 0, 32, s[14:15]
	v_ldexp_f32 v89, v92, v89
	v_cndmask_b32_e64 v81, 0, 32, vcc
	v_ldexp_f32 v81, v88, v81
	v_log_f32_e32 v81, v81
	v_log_f32_e32 v89, v89
	v_mul_f32_e64 v86, |v66|, s69
	v_exp_f32_e32 v90, v86
	v_mul_f32_e32 v97, 0x3f317217, v81
	v_mul_f32_e32 v98, 0x3f317217, v89
	v_fma_f32 v97, v81, s75, -v97
	v_fma_f32 v98, v89, s75, -v98
	v_fmac_f32_e32 v97, 0x3377d1cf, v81
	v_rcp_f32_e32 v86, v88
	v_cndmask_b32_e32 v88, 0, v226, vcc
	v_fmac_f32_e32 v98, 0x3377d1cf, v89
	v_fmac_f32_e32 v97, 0x3f317217, v81
	v_cmp_lt_f32_e64 vcc, |v81|, s63
	v_max_f32_e32 v87, v66, v66
	v_add_f32_e32 v93, 1.0, v90
	v_fmac_f32_e32 v98, 0x3f317217, v89
	v_cndmask_b32_e32 v81, v81, v97, vcc
	v_cmp_lt_f32_e64 vcc, |v89|, s63
	v_min_f32_e32 v80, 0, v87
	v_rcp_f32_e32 v87, v92
	v_cmp_gt_f32_e64 s[16:17], s74, v93
	v_cndmask_b32_e64 v92, 0, v226, s[14:15]
	v_cndmask_b32_e32 v89, v89, v98, vcc
	v_cndmask_b32_e64 v95, 0, 32, s[16:17]
	v_sub_f32_e32 v88, v81, v88
	v_sub_f32_e32 v89, v89, v92
	v_ldexp_f32 v95, v93, v95
	v_pk_add_f32 v[84:85], v[84:85], v[88:89] neg_lo:[0,1] neg_hi:[0,1]
	v_log_f32_e32 v95, v95
	v_add_f32_e32 v94, 1.0, v91
	v_cndmask_b32_e64 v96, 0, v226, s[16:17]
	s_mov_b64 s[0:1], 0
	v_mul_f32_e32 v99, 0x3f317217, v95
	v_fma_f32 v99, v95, s75, -v99
	v_fmac_f32_e32 v99, 0x3377d1cf, v95
	v_fmac_f32_e32 v99, 0x3f317217, v95
	v_cmp_lt_f32_e64 vcc, |v95|, s63
	s_waitcnt vmcnt(0)
	v_pk_add_f32 v[84:85], v[84:85], v[56:57]
	s_nop 0
	v_pk_add_f32 v[56:57], v[84:85], v[52:53] neg_lo:[0,1] neg_hi:[0,1]
	v_max_f32_e32 v81, v52, v52
	v_mul_f32_e64 v52, |v56|, s69
	v_max_f32_e32 v88, v53, v53
	v_mul_f32_e64 v53, |v57|, s69
	v_exp_f32_e32 v89, v52
	v_exp_f32_e32 v92, v53
	v_max_f32_e32 v52, v84, v81
	v_cndmask_b32_e32 v95, v95, v99, vcc
	v_add_f32_e32 v81, 1.0, v89
	v_add_f32_e32 v84, 1.0, v92
	v_cmp_gt_f32_e32 vcc, s74, v81
	v_max_f32_e32 v53, v85, v88
	v_cmp_gt_f32_e64 s[14:15], s74, v84
	v_cndmask_b32_e64 v85, 0, 32, vcc
	v_ldexp_f32 v81, v81, v85
	v_cndmask_b32_e64 v88, 0, 32, s[14:15]
	v_ldexp_f32 v84, v84, v88
	v_log_f32_e32 v81, v81
	v_log_f32_e32 v84, v84
	v_cndmask_b32_e32 v85, 0, v226, vcc
	v_cndmask_b32_e64 v88, 0, v226, s[14:15]
	v_mul_f32_e32 v89, 0x3f317217, v81
	v_mul_f32_e32 v92, 0x3f317217, v84
	v_fma_f32 v89, v81, s75, -v89
	v_fma_f32 v92, v84, s75, -v92
	v_fmac_f32_e32 v89, 0x3377d1cf, v81
	v_fmac_f32_e32 v92, 0x3377d1cf, v84
	v_fmac_f32_e32 v89, 0x3f317217, v81
	v_cmp_lt_f32_e64 vcc, |v81|, s63
	v_fmac_f32_e32 v92, 0x3f317217, v84
	v_pk_mul_f32 v[60:61], v[82:83], v[60:61]
	v_cndmask_b32_e32 v81, v81, v89, vcc
	v_cmp_lt_f32_e64 vcc, |v84|, s63
	v_sub_f32_e32 v89, v81, v85
	v_pk_mul_f32 v[60:61], v[86:87], v[60:61]
	v_cndmask_b32_e32 v84, v84, v92, vcc
	v_cmp_gt_f32_e32 vcc, s74, v94
	v_sub_f32_e32 v88, v84, v88
	v_sub_f32_e32 v84, v95, v96
	v_cndmask_b32_e64 v81, 0, 32, vcc
	v_ldexp_f32 v81, v94, v81
	v_log_f32_e32 v85, v81
	v_max_f32_e32 v81, v67, v67
	v_min_f32_e32 v81, 0, v81
	v_rcp_f32_e32 v82, v93
	v_mul_f32_e32 v92, 0x3f317217, v85
	v_fma_f32 v92, v85, s75, -v92
	v_fmac_f32_e32 v92, 0x3377d1cf, v85
	v_fmac_f32_e32 v92, 0x3f317217, v85
	v_cmp_lt_f32_e64 s[14:15], |v85|, s63
	s_nop 1
	v_cndmask_b32_e64 v85, v85, v92, s[14:15]
	v_cndmask_b32_e32 v92, 0, v226, vcc
	v_sub_f32_e32 v85, v85, v92
	v_pk_add_f32 v[80:81], v[80:81], v[84:85] neg_lo:[0,1] neg_hi:[0,1]
	s_nop 0
	v_pk_add_f32 v[58:59], v[80:81], v[58:59]
	s_nop 0
	v_pk_add_f32 v[80:81], v[58:59], v[54:55] neg_lo:[0,1] neg_hi:[0,1]
	v_mul_f32_e64 v84, |v80|, s69
	v_exp_f32_e32 v84, v84
	v_mul_f32_e64 v85, |v81|, s69
	v_exp_f32_e32 v85, v85
	v_max_f32_e32 v54, v58, v54
	v_add_f32_e32 v83, 1.0, v84
	v_cmp_gt_f32_e32 vcc, s74, v83
	v_add_f32_e32 v85, 1.0, v85
	s_nop 0
	v_cndmask_b32_e64 v84, 0, 32, vcc
	v_ldexp_f32 v83, v83, v84
	v_log_f32_e32 v84, v83
	v_max_f32_e32 v55, v59, v55
	v_rcp_f32_e32 v83, v94
	v_mul_f32_e32 v58, 0x3f317217, v84
	v_fma_f32 v58, v84, s75, -v58
	v_fmac_f32_e32 v58, 0x3377d1cf, v84
	v_fmac_f32_e32 v58, 0x3f317217, v84
	v_cmp_lt_f32_e64 s[14:15], |v84|, s63
	s_nop 1
	v_cndmask_b32_e64 v58, v84, v58, s[14:15]
	v_cndmask_b32_e32 v84, 0, v226, vcc
	v_cmp_gt_f32_e32 vcc, s74, v85
	v_sub_f32_e32 v58, v58, v84
	s_nop 0
	v_cndmask_b32_e64 v86, 0, 32, vcc
	v_ldexp_f32 v85, v85, v86
	v_log_f32_e32 v85, v85
	v_cndmask_b32_e32 v84, 0, v226, vcc
	v_cmp_lt_f32_e64 vcc, |v57|, s49
	v_mul_f32_e32 v59, 0x3f317217, v85
	v_fma_f32 v59, v85, s75, -v59
	v_fmac_f32_e32 v59, 0x3377d1cf, v85
	v_fmac_f32_e32 v59, 0x3f317217, v85
	v_cmp_lt_f32_e64 s[14:15], |v85|, s63
	v_cndmask_b32_e32 v57, 0, v88, vcc
	v_cmp_lt_f32_e64 vcc, |v56|, s49
	v_cndmask_b32_e64 v59, v85, v59, s[14:15]
	v_sub_f32_e32 v59, v59, v84
	v_cndmask_b32_e32 v56, 0, v89, vcc
	v_cmp_lt_f32_e64 vcc, |v81|, s49
	v_pk_add_f32 v[52:53], v[52:53], v[56:57]
	s_nop 0
	v_cndmask_b32_e32 v59, 0, v59, vcc
	v_cmp_lt_f32_e64 vcc, |v80|, s49
	s_nop 1
	v_cndmask_b32_e32 v58, 0, v58, vcc
	v_cmp_lt_f32_e32 vcc, 0, v67
	v_pk_add_f32 v[54:55], v[54:55], v[58:59]
	v_lshl_add_u64 v[58:59], v[108:109], 2, s[94:95]
	v_cndmask_b32_e32 v57, 1.0, v91, vcc
	v_cmp_lt_f32_e32 vcc, 0, v66
	global_store_dwordx4 v[58:59], v[52:55], off
	s_nop 0
	v_cndmask_b32_e32 v56, 1.0, v90, vcc
	v_pk_mul_f32 v[56:57], v[56:57], v[62:63]
	v_lshl_add_u64 v[52:53], v[108:109], 1, s[84:85]
	v_pk_mul_f32 v[56:57], v[82:83], v[56:57]
	v_cvt_pk_bf16_f32 v54, v60, v61
	v_cvt_pk_bf16_f32 v55, v56, v57
	global_store_dwordx2 v[52:53], v[54:55], off

.LBB0_1409:
	s_and_b64 vcc, exec, s[0:1]
	s_cbranch_vccz .LBB0_1426
	s_and_b64 vcc, exec, s[10:11]
	s_mov_b64 s[0:1], -1
	s_cbranch_vccnz .LBB0_1412
	v_lshlrev_b32_e32 v36, 2, v194
	global_load_dwordx4 v[76:79], v36, s[86:87]
	global_load_dwordx4 v[64:67], v36, s[66:67]
	global_load_dwordx4 v[80:83], v36, s[56:57]
	v_mul_f32_e64 v37, |v60|, s69
	v_mul_f32_e64 v41, |v61|, s69
	v_exp_f32_e32 v37, v37
	v_exp_f32_e32 v54, v41
	v_mul_f32_e64 v45, |v62|, s69
	v_max_f32_e32 v50, v62, v62
	v_cmp_lt_f32_e32 vcc, 0, v61
	v_max_f32_e32 v44, v61, v61
	v_mul_f32_e64 v51, |v63|, s69
	v_exp_f32_e32 v84, v45
	v_min_f32_e32 v36, 0, v50
	v_add_f32_e32 v50, 1.0, v37
	v_cndmask_b32_e32 v45, 1.0, v54, vcc
	v_cmp_lt_f32_e32 vcc, 0, v60
	v_min_f32_e32 v41, 0, v44
	v_exp_f32_e32 v85, v51
	v_add_f32_e32 v51, 1.0, v54
	v_cndmask_b32_e32 v44, 1.0, v37, vcc
	v_cmp_gt_f32_e32 vcc, s74, v50
	v_cmp_gt_f32_e64 s[14:15], s74, v51
	v_rcp_f32_e32 v55, v51
	v_cndmask_b32_e64 v37, 0, 32, vcc
	v_cndmask_b32_e64 v58, 0, 32, s[14:15]
	v_ldexp_f32 v37, v50, v37
	v_ldexp_f32 v51, v51, v58
	v_log_f32_e32 v37, v37
	v_log_f32_e32 v51, v51
	v_rcp_f32_e32 v54, v50
	v_cndmask_b32_e32 v50, 0, v226, vcc
	v_mul_f32_e32 v94, 0x3f317217, v37
	v_mul_f32_e32 v95, 0x3f317217, v51
	v_fma_f32 v94, v37, s75, -v94
	v_fma_f32 v95, v51, s75, -v95
	v_fmac_f32_e32 v94, 0x3377d1cf, v37
	v_fmac_f32_e32 v95, 0x3377d1cf, v51
	v_fmac_f32_e32 v94, 0x3f317217, v37
	v_cmp_lt_f32_e64 vcc, |v37|, s63
	v_add_f32_e32 v86, 1.0, v84
	v_fmac_f32_e32 v95, 0x3f317217, v51
	v_cndmask_b32_e32 v37, v37, v94, vcc
	v_cmp_lt_f32_e64 vcc, |v51|, s63
	v_max_f32_e32 v40, v60, v60
	v_cmp_gt_f32_e64 s[16:17], s74, v86
	v_cndmask_b32_e64 v58, 0, v226, s[14:15]
	v_cndmask_b32_e32 v51, v51, v95, vcc
	v_min_f32_e32 v40, 0, v40
	v_cndmask_b32_e64 v59, 0, 32, s[16:17]
	v_sub_f32_e32 v50, v37, v50
	v_sub_f32_e32 v51, v51, v58
	v_ldexp_f32 v59, v86, v59
	v_pk_add_f32 v[40:41], v[40:41], v[50:51] neg_lo:[0,1] neg_hi:[0,1]
	v_log_f32_e32 v59, v59
	v_add_f32_e32 v87, 1.0, v85
	v_cndmask_b32_e64 v91, 0, v226, s[16:17]
	s_mov_b64 s[0:1], 0
	v_mul_f32_e32 v96, 0x3f317217, v59
	v_fma_f32 v96, v59, s75, -v96
	v_fmac_f32_e32 v96, 0x3377d1cf, v59
	v_fmac_f32_e32 v96, 0x3f317217, v59
	v_cmp_lt_f32_e64 vcc, |v59|, s63
	s_waitcnt vmcnt(0)
	v_pk_add_f32 v[40:41], v[40:41], v[76:77]
	s_nop 0
	v_pk_add_f32 v[50:51], v[40:41], v[64:65] neg_lo:[0,1] neg_hi:[0,1]
	v_max_f32_e32 v37, v64, v64
	v_mul_f32_e64 v64, |v50|, s69
	v_max_f32_e32 v58, v65, v65
	v_mul_f32_e64 v65, |v51|, s69
	v_exp_f32_e32 v64, v64
	v_exp_f32_e32 v65, v65
	v_max_f32_e32 v40, v40, v37
	v_cndmask_b32_e32 v59, v59, v96, vcc
	v_add_f32_e32 v37, 1.0, v64
	v_max_f32_e32 v41, v41, v58
	v_add_f32_e32 v58, 1.0, v65
	v_cmp_gt_f32_e32 vcc, s74, v37
	v_cmp_gt_f32_e64 s[14:15], s74, v58
	s_nop 0
	v_cndmask_b32_e64 v64, 0, 32, vcc
	v_cndmask_b32_e64 v65, 0, 32, s[14:15]
	v_ldexp_f32 v37, v37, v64
	v_ldexp_f32 v58, v58, v65
	v_log_f32_e32 v37, v37
	v_log_f32_e32 v58, v58
	v_cndmask_b32_e32 v64, 0, v226, vcc
	v_cndmask_b32_e64 v65, 0, v226, s[14:15]
	v_mul_f32_e32 v76, 0x3f317217, v37
	v_mul_f32_e32 v77, 0x3f317217, v58
	v_fma_f32 v76, v37, s75, -v76
	v_fma_f32 v77, v58, s75, -v77
	v_fmac_f32_e32 v76, 0x3377d1cf, v37
	v_fmac_f32_e32 v77, 0x3377d1cf, v58
	v_fmac_f32_e32 v76, 0x3f317217, v37
	v_cmp_lt_f32_e64 vcc, |v37|, s63
	v_fmac_f32_e32 v77, 0x3f317217, v58
	s_nop 0
	v_cndmask_b32_e32 v37, v37, v76, vcc
	v_cmp_lt_f32_e64 vcc, |v58|, s63
	v_sub_f32_e32 v76, v37, v64
	s_nop 0
	v_cndmask_b32_e32 v58, v58, v77, vcc
	v_cmp_gt_f32_e32 vcc, s74, v87
	v_sub_f32_e32 v77, v58, v65
	v_sub_f32_e32 v58, v59, v91
	v_cndmask_b32_e64 v37, 0, 32, vcc
	v_ldexp_f32 v37, v87, v37
	v_log_f32_e32 v64, v37
	v_max_f32_e32 v37, v63, v63
	v_min_f32_e32 v37, 0, v37
	v_mul_f32_e32 v59, 0x3f317217, v64
	v_fma_f32 v59, v64, s75, -v59
	v_fmac_f32_e32 v59, 0x3377d1cf, v64
	v_fmac_f32_e32 v59, 0x3f317217, v64
	v_cmp_lt_f32_e64 s[14:15], |v64|, s63
	s_nop 1
	v_cndmask_b32_e64 v59, v64, v59, s[14:15]
	v_cndmask_b32_e32 v64, 0, v226, vcc
	v_sub_f32_e32 v59, v59, v64
	v_pk_add_f32 v[36:37], v[36:37], v[58:59] neg_lo:[0,1] neg_hi:[0,1]
	s_nop 0
	v_pk_add_f32 v[58:59], v[36:37], v[78:79]
	s_nop 0
	v_pk_add_f32 v[64:65], v[58:59], v[66:67] neg_lo:[0,1] neg_hi:[0,1]
	s_nop 0
	v_mul_f32_e64 v36, |v64|, s69
	v_exp_f32_e32 v78, v36
	v_pk_mul_f32 v[36:37], v[44:45], v[80:81]
	v_rcp_f32_e32 v44, v86
	v_pk_mul_f32 v[36:37], v[54:55], v[36:37]
	v_add_f32_e32 v45, 1.0, v78
	v_cmp_gt_f32_e32 vcc, s74, v45
	s_nop 1
	v_cndmask_b32_e64 v54, 0, 32, vcc
	v_ldexp_f32 v45, v45, v54
	v_log_f32_e32 v55, v45
	v_max_f32_e32 v54, v66, v66
	v_mul_f32_e64 v66, |v65|, s69
	v_exp_f32_e32 v66, v66
	v_max_f32_e32 v54, v58, v54
	v_mul_f32_e32 v58, 0x3f317217, v55
	v_fma_f32 v58, v55, s75, -v58
	v_fmac_f32_e32 v58, 0x3377d1cf, v55
	v_fmac_f32_e32 v58, 0x3f317217, v55
	v_cmp_lt_f32_e64 s[14:15], |v55|, s63
	v_add_f32_e32 v66, 1.0, v66
	v_rcp_f32_e32 v45, v87
	v_cndmask_b32_e64 v55, v55, v58, s[14:15]
	v_cndmask_b32_e32 v58, 0, v226, vcc
	v_cmp_gt_f32_e32 vcc, s74, v66
	v_sub_f32_e32 v58, v55, v58
	s_nop 0
	v_cndmask_b32_e64 v78, 0, 32, vcc
	v_ldexp_f32 v66, v66, v78
	v_log_f32_e32 v66, v66
	v_max_f32_e32 v55, v59, v67
	v_mul_f32_e32 v59, 0x3f317217, v66
	v_fma_f32 v59, v66, s75, -v59
	v_fmac_f32_e32 v59, 0x3377d1cf, v66
	v_fmac_f32_e32 v59, 0x3f317217, v66
	v_cmp_lt_f32_e64 s[14:15], |v66|, s63
	s_nop 1
	v_cndmask_b32_e64 v59, v66, v59, s[14:15]
	v_cndmask_b32_e32 v66, 0, v226, vcc
	v_cmp_lt_f32_e64 vcc, |v51|, s49
	v_sub_f32_e32 v59, v59, v66
	s_nop 0
	v_cndmask_b32_e32 v51, 0, v77, vcc
	v_cmp_lt_f32_e64 vcc, |v50|, s49
	s_nop 1
	v_cndmask_b32_e32 v50, 0, v76, vcc
	v_cmp_lt_f32_e64 vcc, |v65|, s49
	s_nop 1
	v_cndmask_b32_e32 v59, 0, v59, vcc
	v_cmp_lt_f32_e64 vcc, |v64|, s49
	v_pk_add_f32 v[64:65], v[40:41], v[50:51]
	s_nop 0
	v_cndmask_b32_e32 v58, 0, v58, vcc
	v_cmp_lt_f32_e32 vcc, 0, v63
	v_pk_add_f32 v[66:67], v[54:55], v[58:59]
	s_nop 0
	v_cndmask_b32_e32 v41, 1.0, v85, vcc
	v_cmp_lt_f32_e32 vcc, 0, v62
	s_nop 1
	v_cndmask_b32_e32 v40, 1.0, v84, vcc
	v_pk_mul_f32 v[40:41], v[40:41], v[82:83]
	s_nop 0
	v_pk_mul_f32 v[40:41], v[44:45], v[40:41]
	v_lshl_add_u64 v[44:45], v[92:93], 2, s[94:95]
	global_store_dwordx4 v[44:45], v[64:67], off

.LBB0_1422:
	s_add_u32 s0, s22, s0
	s_addc_u32 s1, s23, s1
	v_mov_b32_e32 v91, v90
	v_lshl_add_u64 v[36:37], v[36:37], 1, s[0:1]
	v_cvt_pk_bf16_f32 v40, v40, v41
	v_cvt_pk_bf16_f32 v41, v42, v43
	v_or_b32_e32 v88, v88, v168
	v_pk_mul_f32 v[50:51], v[38:39], v[90:91]
	s_and_b64 vcc, exec, s[10:11]
	s_mov_b64 s[0:1], -1
	global_store_dwordx2 v[36:37], v[40:41], off offset:16
	s_cbranch_vccnz .LBB0_1424
	v_lshlrev_b32_e32 v36, 2, v194
	v_lshlrev_b32_e32 v44, 2, v168
	global_load_dwordx4 v[40:43], v36, s[86:87] offset:48
	s_nop 0
	global_load_dwordx4 v[36:39], v44, s[66:67]
	v_mul_f32_e64 v52, |v48|, s69
	global_load_dwordx4 v[44:47], v44, s[56:57]
	v_max_f32_e32 v53, v48, v48
	v_mul_f32_e64 v54, |v49|, s69
	v_exp_f32_e32 v62, v52
	v_min_f32_e32 v60, 0, v53
	v_exp_f32_e32 v53, v54
	v_max_f32_e32 v55, v49, v49
	v_cmp_lt_f32_e32 vcc, 0, v49
	v_min_f32_e32 v61, 0, v55
	v_add_f32_e32 v63, 1.0, v62
	v_cndmask_b32_e32 v55, 1.0, v53, vcc
	v_cmp_lt_f32_e32 vcc, 0, v48
	v_add_f32_e32 v64, 1.0, v53
	v_cmp_gt_f32_e64 s[14:15], s74, v64
	v_cndmask_b32_e32 v54, 1.0, v62, vcc
	v_cmp_gt_f32_e32 vcc, s74, v63
	v_cndmask_b32_e64 v62, 0, 32, s[14:15]
	v_ldexp_f32 v62, v64, v62
	v_cndmask_b32_e64 v53, 0, 32, vcc
	v_ldexp_f32 v53, v63, v53
	v_log_f32_e32 v53, v53
	v_log_f32_e32 v62, v62
	v_mul_f32_e64 v56, |v50|, s69
	v_exp_f32_e32 v58, v56
	v_mul_f32_e32 v77, 0x3f317217, v53
	v_mul_f32_e32 v78, 0x3f317217, v62
	v_fma_f32 v77, v53, s75, -v77
	v_fma_f32 v78, v62, s75, -v78
	v_fmac_f32_e32 v77, 0x3377d1cf, v53
	v_rcp_f32_e32 v56, v63
	v_cndmask_b32_e32 v63, 0, v226, vcc
	v_fmac_f32_e32 v78, 0x3377d1cf, v62
	v_fmac_f32_e32 v77, 0x3f317217, v53
	v_cmp_lt_f32_e64 vcc, |v53|, s63
	v_max_f32_e32 v57, v50, v50
	v_add_f32_e32 v65, 1.0, v58
	v_fmac_f32_e32 v78, 0x3f317217, v62
	v_cndmask_b32_e32 v53, v53, v77, vcc
	v_cmp_lt_f32_e64 vcc, |v62|, s63
	v_min_f32_e32 v52, 0, v57
	v_rcp_f32_e32 v57, v64
	v_cmp_gt_f32_e64 s[16:17], s74, v65
	v_cndmask_b32_e64 v64, 0, v226, s[14:15]
	v_cndmask_b32_e32 v77, v62, v78, vcc
	v_cndmask_b32_e64 v67, 0, 32, s[16:17]
	v_sub_f32_e32 v62, v53, v63
	v_sub_f32_e32 v63, v77, v64
	v_ldexp_f32 v67, v65, v67
	v_pk_add_f32 v[60:61], v[60:61], v[62:63] neg_lo:[0,1] neg_hi:[0,1]
	v_log_f32_e32 v67, v67
	v_mul_f32_e64 v59, |v51|, s69
	v_exp_f32_e32 v59, v59
	v_cndmask_b32_e64 v76, 0, v226, s[16:17]
	v_mul_f32_e32 v79, 0x3f317217, v67
	v_fma_f32 v79, v67, s75, -v79
	v_fmac_f32_e32 v79, 0x3377d1cf, v67
	v_fmac_f32_e32 v79, 0x3f317217, v67
	v_cmp_lt_f32_e64 vcc, |v67|, s63
	v_add_f32_e32 v66, 1.0, v59
	s_mov_b64 s[0:1], 0
	v_cndmask_b32_e32 v67, v67, v79, vcc
	s_waitcnt vmcnt(0)
	v_pk_add_f32 v[60:61], v[60:61], v[40:41]
	s_nop 0
	v_pk_add_f32 v[40:41], v[60:61], v[36:37] neg_lo:[0,1] neg_hi:[0,1]
	v_max_f32_e32 v53, v36, v36
	v_mul_f32_e64 v36, |v40|, s69
	v_max_f32_e32 v62, v37, v37
	v_mul_f32_e64 v37, |v41|, s69
	v_exp_f32_e32 v63, v36
	v_exp_f32_e32 v64, v37
	v_max_f32_e32 v36, v60, v53
	v_max_f32_e32 v37, v61, v62
	v_add_f32_e32 v53, 1.0, v63
	v_add_f32_e32 v60, 1.0, v64
	v_cmp_gt_f32_e32 vcc, s74, v53
	v_cmp_gt_f32_e64 s[14:15], s74, v60
	v_pk_mul_f32 v[44:45], v[54:55], v[44:45]
	v_cndmask_b32_e64 v61, 0, 32, vcc
	v_cndmask_b32_e64 v62, 0, 32, s[14:15]
	v_ldexp_f32 v53, v53, v61
	v_ldexp_f32 v60, v60, v62
	v_log_f32_e32 v53, v53
	v_log_f32_e32 v60, v60
	v_cndmask_b32_e32 v61, 0, v226, vcc
	v_cndmask_b32_e64 v62, 0, v226, s[14:15]
	v_mul_f32_e32 v63, 0x3f317217, v53
	v_mul_f32_e32 v64, 0x3f317217, v60
	v_fma_f32 v63, v53, s75, -v63
	v_fma_f32 v64, v60, s75, -v64
	v_fmac_f32_e32 v63, 0x3377d1cf, v53
	v_fmac_f32_e32 v64, 0x3377d1cf, v60
	v_fmac_f32_e32 v63, 0x3f317217, v53
	v_cmp_lt_f32_e64 vcc, |v53|, s63
	v_fmac_f32_e32 v64, 0x3f317217, v60
	v_pk_mul_f32 v[44:45], v[56:57], v[44:45]
	v_cndmask_b32_e32 v53, v53, v63, vcc
	v_cmp_lt_f32_e64 vcc, |v60|, s63
	v_sub_f32_e32 v63, v53, v61
	v_rcp_f32_e32 v54, v65
	v_cndmask_b32_e32 v60, v60, v64, vcc
	v_cmp_gt_f32_e32 vcc, s74, v66
	v_sub_f32_e32 v62, v60, v62
	v_sub_f32_e32 v60, v67, v76
	v_cndmask_b32_e64 v53, 0, 32, vcc
	v_ldexp_f32 v53, v66, v53
	v_log_f32_e32 v61, v53
	v_max_f32_e32 v53, v51, v51
	v_min_f32_e32 v53, 0, v53
	v_mul_f32_e32 v64, 0x3f317217, v61
	v_fma_f32 v64, v61, s75, -v64
	v_fmac_f32_e32 v64, 0x3377d1cf, v61
	v_fmac_f32_e32 v64, 0x3f317217, v61
	v_cmp_lt_f32_e64 s[14:15], |v61|, s63
	s_nop 1
	v_cndmask_b32_e64 v61, v61, v64, s[14:15]
	v_cndmask_b32_e32 v64, 0, v226, vcc
	v_sub_f32_e32 v61, v61, v64
	v_pk_add_f32 v[52:53], v[52:53], v[60:61] neg_lo:[0,1] neg_hi:[0,1]
	s_nop 0
	v_pk_add_f32 v[42:43], v[52:53], v[42:43]
	s_nop 0
	v_pk_add_f32 v[52:53], v[42:43], v[38:39] neg_lo:[0,1] neg_hi:[0,1]
	v_mul_f32_e64 v60, |v52|, s69
	v_exp_f32_e32 v60, v60
	v_mul_f32_e64 v57, |v53|, s69
	v_exp_f32_e32 v57, v57
	v_max_f32_e32 v38, v42, v38
	v_add_f32_e32 v55, 1.0, v60
	v_cmp_gt_f32_e32 vcc, s74, v55
	v_add_f32_e32 v57, 1.0, v57
	s_nop 0
	v_cndmask_b32_e64 v56, 0, 32, vcc
	v_ldexp_f32 v55, v55, v56
	v_log_f32_e32 v56, v55
	v_max_f32_e32 v39, v43, v39
	v_rcp_f32_e32 v55, v66
	v_mul_f32_e32 v42, 0x3f317217, v56
	v_fma_f32 v42, v56, s75, -v42
	v_fmac_f32_e32 v42, 0x3377d1cf, v56
	v_fmac_f32_e32 v42, 0x3f317217, v56
	v_cmp_lt_f32_e64 s[14:15], |v56|, s63
	s_nop 1
	v_cndmask_b32_e64 v42, v56, v42, s[14:15]
	v_cndmask_b32_e32 v56, 0, v226, vcc
	v_cmp_gt_f32_e32 vcc, s74, v57
	v_sub_f32_e32 v42, v42, v56
	s_nop 0
	v_cndmask_b32_e64 v60, 0, 32, vcc
	v_ldexp_f32 v57, v57, v60
	v_log_f32_e32 v57, v57
	v_cndmask_b32_e32 v56, 0, v226, vcc
	v_cmp_lt_f32_e64 vcc, |v41|, s49
	v_mul_f32_e32 v43, 0x3f317217, v57
	v_fma_f32 v43, v57, s75, -v43
	v_fmac_f32_e32 v43, 0x3377d1cf, v57
	v_fmac_f32_e32 v43, 0x3f317217, v57
	v_cmp_lt_f32_e64 s[14:15], |v57|, s63
	v_cndmask_b32_e32 v41, 0, v62, vcc
	v_cmp_lt_f32_e64 vcc, |v40|, s49
	v_cndmask_b32_e64 v43, v57, v43, s[14:15]
	v_sub_f32_e32 v43, v43, v56
	v_cndmask_b32_e32 v40, 0, v63, vcc
	v_cmp_lt_f32_e64 vcc, |v53|, s49
	v_pk_add_f32 v[36:37], v[36:37], v[40:41]
	s_nop 0
	v_cndmask_b32_e32 v43, 0, v43, vcc
	v_cmp_lt_f32_e64 vcc, |v52|, s49
	s_nop 1
	v_cndmask_b32_e32 v42, 0, v42, vcc
	v_cmp_lt_f32_e32 vcc, 0, v51
	v_pk_add_f32 v[38:39], v[38:39], v[42:43]
	v_lshl_add_u64 v[42:43], v[88:89], 2, s[94:95]
	v_cndmask_b32_e32 v41, 1.0, v59, vcc
	v_cmp_lt_f32_e32 vcc, 0, v50
	global_store_dwordx4 v[42:43], v[36:39], off
	s_nop 0
	v_cndmask_b32_e32 v40, 1.0, v58, vcc
	v_pk_mul_f32 v[40:41], v[40:41], v[46:47]
	v_lshl_add_u64 v[36:37], v[88:89], 1, s[84:85]
	v_pk_mul_f32 v[40:41], v[54:55], v[40:41]
	v_cvt_pk_bf16_f32 v38, v44, v45
	v_cvt_pk_bf16_f32 v39, v40, v41
	global_store_dwordx2 v[36:37], v[38:39], off

.LBB0_1445:
	s_and_b64 vcc, exec, s[0:1]
	s_cbranch_vccz .LBB0_1462
	s_and_b64 vcc, exec, s[10:11]
	s_mov_b64 s[0:1], -1
	s_cbranch_vccnz .LBB0_1448
	v_lshlrev_b32_e32 v20, 2, v194
	global_load_dwordx4 v[52:55], v20, s[86:87]
	global_load_dwordx4 v[48:51], v20, s[66:67]
	global_load_dwordx4 v[56:59], v20, s[56:57]
	v_mul_f32_e64 v21, |v44|, s69
	v_max_f32_e32 v24, v44, v44
	v_mul_f32_e64 v25, |v45|, s69
	v_exp_f32_e32 v38, v21
	v_min_f32_e32 v20, 0, v24
	v_exp_f32_e32 v24, v25
	v_mul_f32_e64 v35, |v47|, s69
	v_cmp_lt_f32_e32 vcc, 0, v45
	v_max_f32_e32 v28, v45, v45
	v_mul_f32_e64 v29, |v46|, s69
	v_max_f32_e32 v34, v46, v46
	v_exp_f32_e32 v43, v35
	v_add_f32_e32 v25, 1.0, v38
	v_cndmask_b32_e32 v35, 1.0, v24, vcc
	v_cmp_lt_f32_e32 vcc, 0, v44
	v_min_f32_e32 v21, 0, v28
	v_exp_f32_e32 v42, v29
	v_min_f32_e32 v28, 0, v34
	v_add_f32_e32 v29, 1.0, v24
	v_cndmask_b32_e32 v34, 1.0, v38, vcc
	v_cmp_gt_f32_e32 vcc, s74, v25
	v_cmp_gt_f32_e64 s[14:15], s74, v29
	v_rcp_f32_e32 v39, v29
	v_cndmask_b32_e64 v24, 0, 32, vcc
	v_cndmask_b32_e64 v62, 0, 32, s[14:15]
	v_ldexp_f32 v24, v25, v24
	v_ldexp_f32 v29, v29, v62
	v_log_f32_e32 v24, v24
	v_log_f32_e32 v29, v29
	v_rcp_f32_e32 v38, v25
	v_cndmask_b32_e32 v25, 0, v226, vcc
	v_mul_f32_e32 v74, 0x3f317217, v24
	v_mul_f32_e32 v75, 0x3f317217, v29
	v_fma_f32 v74, v24, s75, -v74
	v_fma_f32 v75, v29, s75, -v75
	v_fmac_f32_e32 v74, 0x3377d1cf, v24
	v_fmac_f32_e32 v75, 0x3377d1cf, v29
	v_fmac_f32_e32 v74, 0x3f317217, v24
	v_cmp_lt_f32_e64 vcc, |v24|, s63
	v_add_f32_e32 v60, 1.0, v42
	v_fmac_f32_e32 v75, 0x3f317217, v29
	v_cndmask_b32_e32 v24, v24, v74, vcc
	v_cmp_lt_f32_e64 vcc, |v29|, s63
	v_cmp_gt_f32_e64 s[16:17], s74, v60
	v_cndmask_b32_e64 v62, 0, v226, s[14:15]
	v_cndmask_b32_e32 v29, v29, v75, vcc
	v_cndmask_b32_e64 v63, 0, 32, s[16:17]
	v_sub_f32_e32 v24, v24, v25
	v_sub_f32_e32 v25, v29, v62
	v_ldexp_f32 v63, v60, v63
	v_pk_add_f32 v[20:21], v[20:21], v[24:25] neg_lo:[0,1] neg_hi:[0,1]
	v_log_f32_e32 v63, v63
	v_add_f32_e32 v61, 1.0, v43
	v_cndmask_b32_e64 v67, 0, v226, s[16:17]
	s_mov_b64 s[0:1], 0
	v_mul_f32_e32 v76, 0x3f317217, v63
	v_fma_f32 v76, v63, s75, -v76
	v_fmac_f32_e32 v76, 0x3377d1cf, v63
	v_fmac_f32_e32 v76, 0x3f317217, v63
	v_cmp_lt_f32_e64 vcc, |v63|, s63
	s_waitcnt vmcnt(0)
	v_pk_add_f32 v[20:21], v[20:21], v[52:53]
	s_nop 0
	v_pk_add_f32 v[24:25], v[20:21], v[48:49] neg_lo:[0,1] neg_hi:[0,1]
	v_max_f32_e32 v29, v48, v48
	v_mul_f32_e64 v48, |v24|, s69
	v_max_f32_e32 v52, v49, v49
	v_mul_f32_e64 v49, |v25|, s69
	v_exp_f32_e32 v48, v48
	v_exp_f32_e32 v49, v49
	v_max_f32_e32 v20, v20, v29
	v_cndmask_b32_e32 v63, v63, v76, vcc
	v_add_f32_e32 v29, 1.0, v48
	v_add_f32_e32 v48, 1.0, v49
	v_cmp_gt_f32_e32 vcc, s74, v29
	v_cmp_gt_f32_e64 s[14:15], s74, v48
	v_max_f32_e32 v21, v21, v52
	v_cndmask_b32_e64 v49, 0, 32, vcc
	v_cndmask_b32_e64 v52, 0, 32, s[14:15]
	v_ldexp_f32 v29, v29, v49
	v_ldexp_f32 v48, v48, v52
	v_log_f32_e32 v29, v29
	v_log_f32_e32 v48, v48
	v_cndmask_b32_e32 v49, 0, v226, vcc
	v_cndmask_b32_e64 v52, 0, v226, s[14:15]
	v_mul_f32_e32 v53, 0x3f317217, v29
	v_mul_f32_e32 v62, 0x3f317217, v48
	v_fma_f32 v53, v29, s75, -v53
	v_fma_f32 v62, v48, s75, -v62
	v_fmac_f32_e32 v53, 0x3377d1cf, v29
	v_fmac_f32_e32 v62, 0x3377d1cf, v48
	v_fmac_f32_e32 v53, 0x3f317217, v29
	v_cmp_lt_f32_e64 vcc, |v29|, s63
	v_fmac_f32_e32 v62, 0x3f317217, v48
	s_nop 0
	v_cndmask_b32_e32 v29, v29, v53, vcc
	v_cmp_lt_f32_e64 vcc, |v48|, s63
	s_nop 1
	v_cndmask_b32_e32 v48, v48, v62, vcc
	v_cmp_gt_f32_e32 vcc, s74, v61
	v_sub_f32_e32 v62, v29, v49
	v_sub_f32_e32 v74, v48, v52
	v_cndmask_b32_e64 v29, 0, 32, vcc
	v_ldexp_f32 v29, v61, v29
	v_log_f32_e32 v49, v29
	v_max_f32_e32 v29, v47, v47
	v_sub_f32_e32 v48, v63, v67
	v_min_f32_e32 v29, 0, v29
	v_mul_f32_e32 v52, 0x3f317217, v49
	v_fma_f32 v52, v49, s75, -v52
	v_fmac_f32_e32 v52, 0x3377d1cf, v49
	v_fmac_f32_e32 v52, 0x3f317217, v49
	v_cmp_lt_f32_e64 s[14:15], |v49|, s63
	s_nop 1
	v_cndmask_b32_e64 v49, v49, v52, s[14:15]
	v_cndmask_b32_e32 v52, 0, v226, vcc
	v_sub_f32_e32 v49, v49, v52
	v_pk_add_f32 v[28:29], v[28:29], v[48:49] neg_lo:[0,1] neg_hi:[0,1]
	s_nop 0
	v_pk_add_f32 v[48:49], v[28:29], v[54:55]
	s_nop 0
	v_pk_add_f32 v[52:53], v[48:49], v[50:51] neg_lo:[0,1] neg_hi:[0,1]
	s_nop 0
	v_mul_f32_e64 v28, |v52|, s69
	v_exp_f32_e32 v54, v28
	v_pk_mul_f32 v[28:29], v[34:35], v[56:57]
	v_rcp_f32_e32 v34, v60
	v_pk_mul_f32 v[28:29], v[38:39], v[28:29]
	v_add_f32_e32 v35, 1.0, v54
	v_cmp_gt_f32_e32 vcc, s74, v35
	s_nop 1
	v_cndmask_b32_e64 v38, 0, 32, vcc
	v_ldexp_f32 v35, v35, v38
	v_log_f32_e32 v39, v35
	v_max_f32_e32 v38, v50, v50
	v_mul_f32_e64 v50, |v53|, s69
	v_exp_f32_e32 v50, v50
	v_max_f32_e32 v38, v48, v38
	v_mul_f32_e32 v48, 0x3f317217, v39
	v_fma_f32 v48, v39, s75, -v48
	v_fmac_f32_e32 v48, 0x3377d1cf, v39
	v_fmac_f32_e32 v48, 0x3f317217, v39
	v_cmp_lt_f32_e64 s[14:15], |v39|, s63
	v_add_f32_e32 v50, 1.0, v50
	v_rcp_f32_e32 v35, v61
	v_cndmask_b32_e64 v39, v39, v48, s[14:15]
	v_cndmask_b32_e32 v48, 0, v226, vcc
	v_cmp_gt_f32_e32 vcc, s74, v50
	v_sub_f32_e32 v48, v39, v48
	s_nop 0
	v_cndmask_b32_e64 v54, 0, 32, vcc
	v_ldexp_f32 v50, v50, v54
	v_log_f32_e32 v50, v50
	v_max_f32_e32 v39, v49, v51
	v_mul_f32_e32 v49, 0x3f317217, v50
	v_fma_f32 v49, v50, s75, -v49
	v_fmac_f32_e32 v49, 0x3377d1cf, v50
	v_fmac_f32_e32 v49, 0x3f317217, v50
	v_cmp_lt_f32_e64 s[14:15], |v50|, s63
	s_nop 1
	v_cndmask_b32_e64 v49, v50, v49, s[14:15]
	v_cndmask_b32_e32 v50, 0, v226, vcc
	v_cmp_lt_f32_e64 vcc, |v25|, s49
	v_sub_f32_e32 v49, v49, v50
	s_nop 0
	v_cndmask_b32_e32 v25, 0, v74, vcc
	v_cmp_lt_f32_e64 vcc, |v24|, s49
	s_nop 1
	v_cndmask_b32_e32 v24, 0, v62, vcc
	v_cmp_lt_f32_e64 vcc, |v53|, s49
	s_nop 1
	v_cndmask_b32_e32 v49, 0, v49, vcc
	v_cmp_lt_f32_e64 vcc, |v52|, s49
	s_nop 1
	v_cndmask_b32_e32 v48, 0, v48, vcc
	v_cmp_lt_f32_e32 vcc, 0, v47
	v_pk_add_f32 v[50:51], v[38:39], v[48:49]
	v_pk_add_f32 v[48:49], v[20:21], v[24:25]
	v_cndmask_b32_e32 v21, 1.0, v43, vcc
	v_cmp_lt_f32_e32 vcc, 0, v46
	v_lshl_add_u64 v[24:25], v[72:73], 2, s[94:95]
	global_store_dwordx4 v[24:25], v[48:51], off
	v_cndmask_b32_e32 v20, 1.0, v42, vcc
	v_pk_mul_f32 v[20:21], v[20:21], v[58:59]
	s_nop 0
	v_pk_mul_f32 v[20:21], v[34:35], v[20:21]

.LBB0_1458:
	s_add_u32 s0, s22, s0
	s_addc_u32 s1, s23, s1
	v_mov_b32_e32 v67, v66
	v_lshl_add_u64 v[20:21], v[20:21], 1, s[0:1]
	v_cvt_pk_bf16_f32 v24, v24, v25
	v_cvt_pk_bf16_f32 v25, v26, v27
	v_or_b32_e32 v64, v64, v168
	v_pk_mul_f32 v[34:35], v[22:23], v[66:67]
	s_and_b64 vcc, exec, s[10:11]
	s_mov_b64 s[0:1], -1
	global_store_dwordx2 v[20:21], v[24:25], off offset:16
	s_cbranch_vccnz .LBB0_1460
	v_lshlrev_b32_e32 v20, 2, v194
	v_lshlrev_b32_e32 v28, 2, v168
	global_load_dwordx4 v[24:27], v20, s[86:87] offset:48
	s_nop 0
	global_load_dwordx4 v[20:23], v28, s[66:67]
	v_mul_f32_e64 v36, |v32|, s69
	global_load_dwordx4 v[28:31], v28, s[56:57]
	v_max_f32_e32 v37, v32, v32
	v_mul_f32_e64 v38, |v33|, s69
	v_exp_f32_e32 v45, v36
	v_min_f32_e32 v40, 0, v37
	v_exp_f32_e32 v37, v38
	v_max_f32_e32 v39, v33, v33
	v_mul_f32_e64 v44, |v35|, s69
	v_cmp_lt_f32_e32 vcc, 0, v33
	v_min_f32_e32 v41, 0, v39
	v_exp_f32_e32 v47, v44
	v_add_f32_e32 v44, 1.0, v45
	v_cndmask_b32_e32 v39, 1.0, v37, vcc
	v_cmp_lt_f32_e32 vcc, 0, v32
	v_add_f32_e32 v48, 1.0, v37
	v_cmp_gt_f32_e64 s[14:15], s74, v48
	v_cndmask_b32_e32 v38, 1.0, v45, vcc
	v_cmp_gt_f32_e32 vcc, s74, v44
	v_cndmask_b32_e64 v45, 0, 32, s[14:15]
	v_ldexp_f32 v45, v48, v45
	v_cndmask_b32_e64 v37, 0, 32, vcc
	v_ldexp_f32 v37, v44, v37
	v_log_f32_e32 v37, v37
	v_log_f32_e32 v45, v45
	v_mul_f32_e64 v42, |v34|, s69
	v_exp_f32_e32 v46, v42
	v_mul_f32_e32 v53, 0x3f317217, v37
	v_mul_f32_e32 v54, 0x3f317217, v45
	v_fma_f32 v53, v37, s75, -v53
	v_fma_f32 v54, v45, s75, -v54
	v_fmac_f32_e32 v53, 0x3377d1cf, v37
	v_rcp_f32_e32 v42, v44
	v_cndmask_b32_e32 v44, 0, v226, vcc
	v_fmac_f32_e32 v54, 0x3377d1cf, v45
	v_fmac_f32_e32 v53, 0x3f317217, v37
	v_cmp_lt_f32_e64 vcc, |v37|, s63
	v_max_f32_e32 v43, v34, v34
	v_add_f32_e32 v49, 1.0, v46
	v_fmac_f32_e32 v54, 0x3f317217, v45
	v_cndmask_b32_e32 v37, v37, v53, vcc
	v_cmp_lt_f32_e64 vcc, |v45|, s63
	v_min_f32_e32 v36, 0, v43
	v_rcp_f32_e32 v43, v48
	v_cmp_gt_f32_e64 s[16:17], s74, v49
	v_cndmask_b32_e64 v48, 0, v226, s[14:15]
	v_cndmask_b32_e32 v45, v45, v54, vcc
	v_cndmask_b32_e64 v51, 0, 32, s[16:17]
	v_sub_f32_e32 v44, v37, v44
	v_sub_f32_e32 v45, v45, v48
	v_ldexp_f32 v51, v49, v51
	v_pk_add_f32 v[40:41], v[40:41], v[44:45] neg_lo:[0,1] neg_hi:[0,1]
	v_log_f32_e32 v51, v51
	v_add_f32_e32 v50, 1.0, v47
	v_cndmask_b32_e64 v52, 0, v226, s[16:17]
	s_mov_b64 s[0:1], 0
	v_mul_f32_e32 v55, 0x3f317217, v51
	v_fma_f32 v55, v51, s75, -v55
	v_fmac_f32_e32 v55, 0x3377d1cf, v51
	v_fmac_f32_e32 v55, 0x3f317217, v51
	v_cmp_lt_f32_e64 vcc, |v51|, s63
	s_waitcnt vmcnt(0)
	v_pk_add_f32 v[40:41], v[40:41], v[24:25]
	s_nop 0
	v_pk_add_f32 v[24:25], v[40:41], v[20:21] neg_lo:[0,1] neg_hi:[0,1]
	v_max_f32_e32 v37, v20, v20
	v_mul_f32_e64 v20, |v24|, s69
	v_max_f32_e32 v44, v21, v21
	v_mul_f32_e64 v21, |v25|, s69
	v_exp_f32_e32 v45, v20
	v_exp_f32_e32 v48, v21
	v_max_f32_e32 v20, v40, v37
	v_cndmask_b32_e32 v51, v51, v55, vcc
	v_add_f32_e32 v37, 1.0, v45
	v_add_f32_e32 v40, 1.0, v48
	v_cmp_gt_f32_e32 vcc, s74, v37
	v_max_f32_e32 v21, v41, v44
	v_cmp_gt_f32_e64 s[14:15], s74, v40
	v_cndmask_b32_e64 v41, 0, 32, vcc
	v_ldexp_f32 v37, v37, v41
	v_cndmask_b32_e64 v44, 0, 32, s[14:15]
	v_ldexp_f32 v40, v40, v44
	v_log_f32_e32 v37, v37
	v_log_f32_e32 v40, v40
	v_cndmask_b32_e32 v41, 0, v226, vcc
	v_cndmask_b32_e64 v44, 0, v226, s[14:15]
	v_mul_f32_e32 v45, 0x3f317217, v37
	v_mul_f32_e32 v48, 0x3f317217, v40
	v_fma_f32 v45, v37, s75, -v45
	v_fma_f32 v48, v40, s75, -v48
	v_fmac_f32_e32 v45, 0x3377d1cf, v37
	v_fmac_f32_e32 v48, 0x3377d1cf, v40
	v_fmac_f32_e32 v45, 0x3f317217, v37
	v_cmp_lt_f32_e64 vcc, |v37|, s63
	v_fmac_f32_e32 v48, 0x3f317217, v40
	v_pk_mul_f32 v[28:29], v[38:39], v[28:29]
	v_cndmask_b32_e32 v37, v37, v45, vcc
	v_cmp_lt_f32_e64 vcc, |v40|, s63
	v_sub_f32_e32 v45, v37, v41
	v_pk_mul_f32 v[28:29], v[42:43], v[28:29]
	v_cndmask_b32_e32 v40, v40, v48, vcc
	v_cmp_gt_f32_e32 vcc, s74, v50
	v_sub_f32_e32 v44, v40, v44
	v_sub_f32_e32 v40, v51, v52
	v_cndmask_b32_e64 v37, 0, 32, vcc
	v_ldexp_f32 v37, v50, v37
	v_log_f32_e32 v41, v37
	v_max_f32_e32 v37, v35, v35
	v_min_f32_e32 v37, 0, v37
	v_rcp_f32_e32 v38, v49
	v_mul_f32_e32 v48, 0x3f317217, v41
	v_fma_f32 v48, v41, s75, -v48
	v_fmac_f32_e32 v48, 0x3377d1cf, v41
	v_fmac_f32_e32 v48, 0x3f317217, v41
	v_cmp_lt_f32_e64 s[14:15], |v41|, s63
	s_nop 1
	v_cndmask_b32_e64 v41, v41, v48, s[14:15]
	v_cndmask_b32_e32 v48, 0, v226, vcc
	v_sub_f32_e32 v41, v41, v48
	v_pk_add_f32 v[36:37], v[36:37], v[40:41] neg_lo:[0,1] neg_hi:[0,1]
	s_nop 0
	v_pk_add_f32 v[26:27], v[36:37], v[26:27]
	s_nop 0
	v_pk_add_f32 v[36:37], v[26:27], v[22:23] neg_lo:[0,1] neg_hi:[0,1]
	v_mul_f32_e64 v40, |v36|, s69
	v_exp_f32_e32 v40, v40
	v_mul_f32_e64 v41, |v37|, s69
	v_exp_f32_e32 v41, v41
	v_max_f32_e32 v22, v26, v22
	v_add_f32_e32 v39, 1.0, v40
	v_cmp_gt_f32_e32 vcc, s74, v39
	v_add_f32_e32 v41, 1.0, v41
	s_nop 0
	v_cndmask_b32_e64 v40, 0, 32, vcc
	v_ldexp_f32 v39, v39, v40
	v_log_f32_e32 v40, v39
	v_max_f32_e32 v23, v27, v23
	v_rcp_f32_e32 v39, v50
	v_mul_f32_e32 v26, 0x3f317217, v40
	v_fma_f32 v26, v40, s75, -v26
	v_fmac_f32_e32 v26, 0x3377d1cf, v40
	v_fmac_f32_e32 v26, 0x3f317217, v40
	v_cmp_lt_f32_e64 s[14:15], |v40|, s63
	s_nop 1
	v_cndmask_b32_e64 v26, v40, v26, s[14:15]
	v_cndmask_b32_e32 v40, 0, v226, vcc
	v_cmp_gt_f32_e32 vcc, s74, v41
	v_sub_f32_e32 v26, v26, v40
	s_nop 0
	v_cndmask_b32_e64 v42, 0, 32, vcc
	v_ldexp_f32 v41, v41, v42
	v_log_f32_e32 v41, v41
	v_cndmask_b32_e32 v40, 0, v226, vcc
	v_cmp_lt_f32_e64 vcc, |v25|, s49
	v_mul_f32_e32 v27, 0x3f317217, v41
	v_fma_f32 v27, v41, s75, -v27
	v_fmac_f32_e32 v27, 0x3377d1cf, v41
	v_fmac_f32_e32 v27, 0x3f317217, v41
	v_cmp_lt_f32_e64 s[14:15], |v41|, s63
	v_cndmask_b32_e32 v25, 0, v44, vcc
	v_cmp_lt_f32_e64 vcc, |v24|, s49
	v_cndmask_b32_e64 v27, v41, v27, s[14:15]
	v_sub_f32_e32 v27, v27, v40
	v_cndmask_b32_e32 v24, 0, v45, vcc
	v_cmp_lt_f32_e64 vcc, |v37|, s49
	v_pk_add_f32 v[20:21], v[20:21], v[24:25]
	s_nop 0
	v_cndmask_b32_e32 v27, 0, v27, vcc
	v_cmp_lt_f32_e64 vcc, |v36|, s49
	s_nop 1
	v_cndmask_b32_e32 v26, 0, v26, vcc
	v_cmp_lt_f32_e32 vcc, 0, v35
	v_pk_add_f32 v[22:23], v[22:23], v[26:27]
	v_lshl_add_u64 v[26:27], v[64:65], 2, s[94:95]
	v_cndmask_b32_e32 v25, 1.0, v47, vcc
	v_cmp_lt_f32_e32 vcc, 0, v34
	global_store_dwordx4 v[26:27], v[20:23], off
	s_nop 0
	v_cndmask_b32_e32 v24, 1.0, v46, vcc
	v_pk_mul_f32 v[24:25], v[24:25], v[30:31]
	v_lshl_add_u64 v[20:21], v[64:65], 1, s[84:85]
	v_pk_mul_f32 v[24:25], v[38:39], v[24:25]
	v_cvt_pk_bf16_f32 v22, v28, v29
	v_cvt_pk_bf16_f32 v23, v24, v25
	global_store_dwordx2 v[20:21], v[22:23], off

.LBB0_1481:
	s_and_b64 vcc, exec, s[0:1]
	s_cbranch_vccz .LBB0_1498
	s_mov_b64 s[0:1], -1
	s_and_b64 vcc, exec, s[10:11]
	v_lshlrev_b32_e32 v44, 2, v194
	s_cbranch_vccnz .LBB0_1484
	global_load_dwordx4 v[40:43], v44, s[86:87]
	global_load_dwordx4 v[36:39], v44, s[66:67]
	global_load_dwordx4 v[32:35], v44, s[56:57]
	v_mul_f32_e64 v4, |v28|, s69
	v_max_f32_e32 v5, v28, v28
	v_mul_f32_e64 v9, |v29|, s69
	v_exp_f32_e32 v22, v4
	v_min_f32_e32 v8, 0, v5
	v_exp_f32_e32 v5, v9
	v_mul_f32_e64 v13, |v30|, s69
	v_max_f32_e32 v18, v30, v30
	v_cmp_lt_f32_e32 vcc, 0, v29
	v_max_f32_e32 v12, v29, v29
	v_mul_f32_e64 v19, |v31|, s69
	v_exp_f32_e32 v45, v13
	v_min_f32_e32 v4, 0, v18
	v_add_f32_e32 v18, 1.0, v22
	v_cndmask_b32_e32 v13, 1.0, v5, vcc
	v_cmp_lt_f32_e32 vcc, 0, v28
	v_min_f32_e32 v9, 0, v12
	v_exp_f32_e32 v46, v19
	v_add_f32_e32 v19, 1.0, v5
	v_cndmask_b32_e32 v12, 1.0, v22, vcc
	v_cmp_gt_f32_e32 vcc, s74, v18
	v_cmp_gt_f32_e64 s[6:7], s74, v19
	v_rcp_f32_e32 v23, v19
	v_cndmask_b32_e64 v5, 0, 32, vcc
	v_cndmask_b32_e64 v26, 0, 32, s[6:7]
	v_ldexp_f32 v5, v18, v5
	v_ldexp_f32 v19, v19, v26
	v_log_f32_e32 v5, v5
	v_log_f32_e32 v19, v19
	v_rcp_f32_e32 v22, v18
	v_cndmask_b32_e32 v18, 0, v226, vcc
	v_mul_f32_e32 v55, 0x3f317217, v5
	v_mul_f32_e32 v56, 0x3f317217, v19
	v_fma_f32 v55, v5, s75, -v55
	v_fma_f32 v56, v19, s75, -v56
	v_fmac_f32_e32 v55, 0x3377d1cf, v5
	v_fmac_f32_e32 v56, 0x3377d1cf, v19
	v_fmac_f32_e32 v55, 0x3f317217, v5
	v_cmp_lt_f32_e64 vcc, |v5|, s63
	v_add_f32_e32 v47, 1.0, v45
	v_fmac_f32_e32 v56, 0x3f317217, v19
	v_cndmask_b32_e32 v5, v5, v55, vcc
	v_cmp_lt_f32_e64 vcc, |v19|, s63
	v_cmp_gt_f32_e64 s[8:9], s74, v47
	v_cndmask_b32_e64 v26, 0, v226, s[6:7]
	v_cndmask_b32_e32 v19, v19, v56, vcc
	v_cndmask_b32_e64 v27, 0, 32, s[8:9]
	v_sub_f32_e32 v18, v5, v18
	v_sub_f32_e32 v19, v19, v26
	v_ldexp_f32 v27, v47, v27
	v_pk_add_f32 v[8:9], v[8:9], v[18:19] neg_lo:[0,1] neg_hi:[0,1]
	v_log_f32_e32 v27, v27
	v_add_f32_e32 v51, 1.0, v46
	v_cndmask_b32_e64 v54, 0, v226, s[8:9]
	s_mov_b64 s[0:1], 0
	v_mul_f32_e32 v57, 0x3f317217, v27
	v_fma_f32 v57, v27, s75, -v57
	v_fmac_f32_e32 v57, 0x3377d1cf, v27
	v_fmac_f32_e32 v57, 0x3f317217, v27
	v_cmp_lt_f32_e64 vcc, |v27|, s63
	s_waitcnt vmcnt(0)
	v_pk_add_f32 v[8:9], v[8:9], v[40:41]
	s_nop 0
	v_pk_add_f32 v[18:19], v[8:9], v[36:37] neg_lo:[0,1] neg_hi:[0,1]
	v_max_f32_e32 v5, v36, v36
	v_mul_f32_e64 v36, |v18|, s69
	v_max_f32_e32 v26, v37, v37
	v_mul_f32_e64 v37, |v19|, s69
	v_exp_f32_e32 v36, v36
	v_exp_f32_e32 v37, v37
	v_max_f32_e32 v8, v8, v5
	v_cndmask_b32_e32 v27, v27, v57, vcc
	v_add_f32_e32 v5, 1.0, v36
	v_max_f32_e32 v9, v9, v26
	v_add_f32_e32 v26, 1.0, v37
	v_cmp_gt_f32_e32 vcc, s74, v5
	v_cmp_gt_f32_e64 s[6:7], s74, v26
	s_nop 0
	v_cndmask_b32_e64 v36, 0, 32, vcc
	v_cndmask_b32_e64 v37, 0, 32, s[6:7]
	v_ldexp_f32 v5, v5, v36
	v_ldexp_f32 v26, v26, v37
	v_log_f32_e32 v5, v5
	v_log_f32_e32 v26, v26
	v_cndmask_b32_e32 v36, 0, v226, vcc
	v_cndmask_b32_e64 v37, 0, v226, s[6:7]
	v_mul_f32_e32 v40, 0x3f317217, v5
	v_mul_f32_e32 v41, 0x3f317217, v26
	v_fma_f32 v40, v5, s75, -v40
	v_fma_f32 v41, v26, s75, -v41
	v_fmac_f32_e32 v40, 0x3377d1cf, v5
	v_fmac_f32_e32 v41, 0x3377d1cf, v26
	v_fmac_f32_e32 v40, 0x3f317217, v5
	v_cmp_lt_f32_e64 vcc, |v5|, s63
	v_fmac_f32_e32 v41, 0x3f317217, v26
	s_nop 0
	v_cndmask_b32_e32 v5, v5, v40, vcc
	v_cmp_lt_f32_e64 vcc, |v26|, s63
	v_sub_f32_e32 v40, v5, v36
	s_nop 0
	v_cndmask_b32_e32 v26, v26, v41, vcc
	v_cmp_gt_f32_e32 vcc, s74, v51
	v_sub_f32_e32 v41, v26, v37
	v_sub_f32_e32 v26, v27, v54
	v_cndmask_b32_e64 v5, 0, 32, vcc
	v_ldexp_f32 v5, v51, v5
	v_log_f32_e32 v36, v5
	v_max_f32_e32 v5, v31, v31
	v_min_f32_e32 v5, 0, v5
	v_mul_f32_e32 v27, 0x3f317217, v36
	v_fma_f32 v27, v36, s75, -v27
	v_fmac_f32_e32 v27, 0x3377d1cf, v36
	v_fmac_f32_e32 v27, 0x3f317217, v36
	v_cmp_lt_f32_e64 s[6:7], |v36|, s63
	s_nop 1
	v_cndmask_b32_e64 v27, v36, v27, s[6:7]
	v_cndmask_b32_e32 v36, 0, v226, vcc
	v_sub_f32_e32 v27, v27, v36
	v_pk_add_f32 v[4:5], v[4:5], v[26:27] neg_lo:[0,1] neg_hi:[0,1]
	s_nop 0
	v_pk_add_f32 v[26:27], v[4:5], v[42:43]
	s_nop 0
	v_pk_add_f32 v[36:37], v[26:27], v[38:39] neg_lo:[0,1] neg_hi:[0,1]
	s_nop 0
	v_mul_f32_e64 v4, |v36|, s69
	v_exp_f32_e32 v42, v4
	v_pk_mul_f32 v[4:5], v[12:13], v[32:33]
	v_mul_f32_e64 v32, |v37|, s69
	v_pk_mul_f32 v[4:5], v[22:23], v[4:5]
	v_add_f32_e32 v13, 1.0, v42
	v_cmp_gt_f32_e32 vcc, s74, v13
	v_exp_f32_e32 v32, v32
	v_rcp_f32_e32 v12, v47
	v_cndmask_b32_e64 v22, 0, 32, vcc
	v_ldexp_f32 v13, v13, v22
	v_log_f32_e32 v23, v13
	v_max_f32_e32 v22, v26, v38
	v_add_f32_e32 v32, 1.0, v32
	v_mul_f32_e32 v26, 0x3f317217, v23
	v_fma_f32 v26, v23, s75, -v26
	v_fmac_f32_e32 v26, 0x3377d1cf, v23
	v_fmac_f32_e32 v26, 0x3f317217, v23
	v_cmp_lt_f32_e64 s[6:7], |v23|, s63
	v_rcp_f32_e32 v13, v51
	s_nop 0
	v_cndmask_b32_e64 v23, v23, v26, s[6:7]
	v_cndmask_b32_e32 v26, 0, v226, vcc
	v_cmp_gt_f32_e32 vcc, s74, v32
	v_sub_f32_e32 v26, v23, v26
	s_nop 0
	v_cndmask_b32_e64 v33, 0, 32, vcc
	v_ldexp_f32 v32, v32, v33
	v_log_f32_e32 v32, v32
	v_max_f32_e32 v23, v27, v39
	v_mul_f32_e32 v27, 0x3f317217, v32
	v_fma_f32 v27, v32, s75, -v27
	v_fmac_f32_e32 v27, 0x3377d1cf, v32
	v_fmac_f32_e32 v27, 0x3f317217, v32
	v_cmp_lt_f32_e64 s[6:7], |v32|, s63
	s_nop 1
	v_cndmask_b32_e64 v27, v32, v27, s[6:7]
	v_cndmask_b32_e32 v32, 0, v226, vcc
	v_cmp_lt_f32_e64 vcc, |v19|, s49
	v_sub_f32_e32 v27, v27, v32
	s_nop 0
	v_cndmask_b32_e32 v19, 0, v41, vcc
	v_cmp_lt_f32_e64 vcc, |v18|, s49
	s_nop 1
	v_cndmask_b32_e32 v18, 0, v40, vcc
	v_cmp_lt_f32_e64 vcc, |v37|, s49
	s_nop 1
	v_cndmask_b32_e32 v27, 0, v27, vcc
	v_cmp_lt_f32_e64 vcc, |v36|, s49
	v_pk_add_f32 v[36:37], v[8:9], v[18:19]
	s_nop 0
	v_cndmask_b32_e32 v26, 0, v26, vcc
	v_cmp_lt_f32_e32 vcc, 0, v31
	v_pk_add_f32 v[38:39], v[22:23], v[26:27]
	s_nop 0
	v_cndmask_b32_e32 v9, 1.0, v46, vcc
	v_cmp_lt_f32_e32 vcc, 0, v30
	s_nop 1
	v_cndmask_b32_e32 v8, 1.0, v45, vcc
	v_pk_mul_f32 v[8:9], v[8:9], v[34:35]
	s_nop 0
	v_pk_mul_f32 v[8:9], v[12:13], v[8:9]
	v_lshl_add_u64 v[12:13], v[52:53], 2, s[94:95]
	global_store_dwordx4 v[12:13], v[36:39], off
